# code placement: the eight GEMM K-loop heads and four other hot loop heads aligned to 64 bytes
# speedup vs baseline: 1.0055x; 1.0014x over previous
.LBB0_146:
	s_and_b32 s7, s4, 7
	v_lshl_add_u32 v0, s7, 8, v201
	v_ashrrev_i32_e32 v1, 31, v0
	v_lshlrev_b64 v[0:1], 11, v[0:1]
	s_and_b32 s7, s6, 0xffffff00
	v_lshl_add_u64 v[170:171], v[160:161], 0, v[0:1]
	v_add_u32_e32 v0, s7, v175
	s_and_b32 s7, s10, 7
	v_ashrrev_i32_e32 v1, 31, v0
	s_or_b32 s7, s7, s5
	v_lshlrev_b64 v[0:1], 11, v[0:1]
	s_lshl_b32 s7, s7, 8
	v_lshl_add_u64 v[172:173], v[168:169], 0, v[0:1]
	v_add_u32_e32 v0, s7, v175
	s_lshl_b32 s11, s10, 5
	v_ashrrev_i32_e32 v1, 31, v0
	s_and_b32 s11, s11, 0xffffff00
	v_add_u32_e32 v2, s11, v175
	v_lshlrev_b64 v[0:1], 11, v[0:1]
	s_waitcnt vmcnt(0) lgkmcnt(0)
	s_barrier
	v_ashrrev_i32_e32 v3, 31, v2
	v_lshl_add_u64 v[0:1], v[154:155], 0, v[0:1]
	v_readfirstlane_b32 s12, v180
	s_mov_b32 m0, s12
	s_nop 0
	global_load_lds_dwordx4 v[0:1], off
	v_lshlrev_b64 v[2:3], 11, v[2:3]
	v_lshl_add_u64 v[4:5], v[0:1], 0, s[34:35]
	s_add_i32 s13, s12, 0x2000
	s_mov_b32 m0, s13
	s_nop 0
	global_load_lds_dwordx4 v[4:5], off
	v_lshl_add_u64 v[2:3], v[156:157], 0, v[2:3]
	s_add_i32 s13, s12, 0x4000
	s_mov_b32 m0, s13
	s_nop 0
	global_load_lds_dwordx4 v[2:3], off
	v_lshl_add_u64 v[4:5], v[2:3], 0, s[34:35]
	s_add_i32 s13, s12, 0x6000
	s_mov_b32 m0, s13
	s_nop 0
	global_load_lds_dwordx4 v[4:5], off
	s_add_i32 s13, s12, 0x8000
	v_lshl_add_u64 v[4:5], v[0:1], 0, 64
	s_mov_b32 m0, s13
	s_nop 0
	global_load_lds_dwordx4 v[4:5], off
	s_mov_b64 s[14:15], 0x40040
	v_lshl_add_u64 v[4:5], v[0:1], 0, s[14:15]
	s_add_i32 s13, s12, 0xa000
	s_mov_b32 m0, s13
	s_nop 0
	global_load_lds_dwordx4 v[4:5], off
	v_lshl_add_u64 v[4:5], v[2:3], 0, 64
	s_add_i32 s13, s12, 0xc000
	s_mov_b32 m0, s13
	s_nop 0
	global_load_lds_dwordx4 v[4:5], off
	v_lshl_add_u64 v[4:5], v[2:3], 0, s[14:15]
	s_add_i32 s13, s12, 0xe000
	s_mov_b32 m0, s13
	s_nop 0
	global_load_lds_dwordx4 v[4:5], off
	s_mov_b64 s[14:15], 0x80
	s_add_i32 s13, s12, 0x10000
	v_lshl_add_u64 v[4:5], v[0:1], 0, s[14:15]
	s_mov_b32 m0, s13
	s_nop 0
	global_load_lds_dwordx4 v[4:5], off
	s_mov_b64 s[16:17], 0x40080
	v_lshl_add_u64 v[0:1], v[0:1], 0, s[16:17]
	s_add_i32 s13, s12, 0x12000
	s_mov_b32 m0, s13
	s_nop 0
	global_load_lds_dwordx4 v[0:1], off
	v_lshl_add_u64 v[0:1], v[2:3], 0, s[14:15]
	s_add_i32 s13, s12, 0x14000
	s_mov_b32 m0, s13
	s_nop 0
	global_load_lds_dwordx4 v[0:1], off
	v_lshl_add_u64 v[0:1], v[2:3], 0, s[16:17]
	s_add_i32 s12, s12, 0x16000
	s_mov_b32 m0, s12
	s_nop 0
	global_load_lds_dwordx4 v[0:1], off
	v_mov_b32_e32 v130, 0
	v_mov_b32_e32 v134, 0
	v_mov_b32_e32 v0, 0
	s_mov_b32 s12, 0x18000
	v_mov_b32_e32 v1, v0
	v_mov_b32_e32 v2, v0
	v_mov_b32_e32 v3, v0
	v_mov_b32_e32 v4, v0
	v_mov_b32_e32 v5, v0
	v_mov_b32_e32 v6, v0
	v_mov_b32_e32 v7, v0
	v_mov_b32_e32 v8, v0
	v_mov_b32_e32 v9, v0
	v_mov_b32_e32 v10, v0
	v_mov_b32_e32 v11, v0
	v_mov_b32_e32 v12, v0
	v_mov_b32_e32 v13, v0
	v_mov_b32_e32 v14, v0
	v_mov_b32_e32 v15, v0
	v_mov_b32_e32 v16, v0
	v_mov_b32_e32 v17, v0
	v_mov_b32_e32 v18, v0
	v_mov_b32_e32 v19, v0
	v_mov_b32_e32 v20, v0
	v_mov_b32_e32 v21, v0
	v_mov_b32_e32 v22, v0
	v_mov_b32_e32 v23, v0
	v_mov_b32_e32 v24, v0
	v_mov_b32_e32 v25, v0
	v_mov_b32_e32 v26, v0
	v_mov_b32_e32 v27, v0
	v_mov_b32_e32 v28, v0
	v_mov_b32_e32 v29, v0
	v_mov_b32_e32 v30, v0
	v_mov_b32_e32 v31, v0
	v_mov_b32_e32 v32, v0
	v_mov_b32_e32 v33, v0
	v_mov_b32_e32 v34, v0
	v_mov_b32_e32 v35, v0
	v_mov_b32_e32 v36, v0
	v_mov_b32_e32 v37, v0
	v_mov_b32_e32 v38, v0
	v_mov_b32_e32 v39, v0
	v_mov_b32_e32 v40, v0
	v_mov_b32_e32 v41, v0
	v_mov_b32_e32 v42, v0
	v_mov_b32_e32 v43, v0
	v_mov_b32_e32 v44, v0
	v_mov_b32_e32 v45, v0
	v_mov_b32_e32 v46, v0
	v_mov_b32_e32 v47, v0
	v_mov_b32_e32 v48, v0
	v_mov_b32_e32 v49, v0
	v_mov_b32_e32 v50, v0
	v_mov_b32_e32 v51, v0
	v_mov_b32_e32 v52, v0
	v_mov_b32_e32 v53, v0
	v_mov_b32_e32 v54, v0
	v_mov_b32_e32 v55, v0
	v_mov_b32_e32 v56, v0
	v_mov_b32_e32 v57, v0
	v_mov_b32_e32 v58, v0
	v_mov_b32_e32 v59, v0
	v_mov_b32_e32 v60, v0
	v_mov_b32_e32 v61, v0
	v_mov_b32_e32 v62, v0
	v_mov_b32_e32 v63, v0
	v_mov_b32_e32 v64, v0
	v_mov_b32_e32 v65, v0
	v_mov_b32_e32 v66, v0
	v_mov_b32_e32 v67, v0
	v_mov_b32_e32 v68, v0
	v_mov_b32_e32 v69, v0
	v_mov_b32_e32 v70, v0
	v_mov_b32_e32 v71, v0
	v_mov_b32_e32 v72, v0
	v_mov_b32_e32 v73, v0
	v_mov_b32_e32 v74, v0
	v_mov_b32_e32 v75, v0
	v_mov_b32_e32 v76, v0
	v_mov_b32_e32 v77, v0
	v_mov_b32_e32 v78, v0
	v_mov_b32_e32 v79, v0
	v_mov_b32_e32 v80, v0
	v_mov_b32_e32 v81, v0
	v_mov_b32_e32 v82, v0
	v_mov_b32_e32 v83, v0
	v_mov_b32_e32 v84, v0
	v_mov_b32_e32 v85, v0
	v_mov_b32_e32 v86, v0
	v_mov_b32_e32 v87, v0
	v_mov_b32_e32 v88, v0
	v_mov_b32_e32 v89, v0
	v_mov_b32_e32 v90, v0
	v_mov_b32_e32 v91, v0
	v_mov_b32_e32 v92, v0
	v_mov_b32_e32 v93, v0
	v_mov_b32_e32 v94, v0
	v_mov_b32_e32 v95, v0
	v_mov_b32_e32 v96, v0
	v_mov_b32_e32 v97, v0
	v_mov_b32_e32 v98, v0
	v_mov_b32_e32 v99, v0
	v_mov_b32_e32 v100, v0
	v_mov_b32_e32 v101, v0
	v_mov_b32_e32 v102, v0
	v_mov_b32_e32 v103, v0
	v_mov_b32_e32 v104, v0
	v_mov_b32_e32 v105, v0
	v_mov_b32_e32 v106, v0
	v_mov_b32_e32 v107, v0
	v_mov_b32_e32 v108, v0
	v_mov_b32_e32 v109, v0
	v_mov_b32_e32 v110, v0
	v_mov_b32_e32 v111, v0
	v_mov_b32_e32 v112, v0
	v_mov_b32_e32 v113, v0
	v_mov_b32_e32 v114, v0
	v_mov_b32_e32 v115, v0
	v_mov_b32_e32 v116, v0
	v_mov_b32_e32 v117, v0
	v_mov_b32_e32 v118, v0
	v_mov_b32_e32 v119, v0
	v_mov_b32_e32 v120, v0
	v_mov_b32_e32 v121, v0
	v_mov_b32_e32 v122, v0
	v_mov_b32_e32 v123, v0
	v_mov_b32_e32 v124, v0
	v_mov_b32_e32 v125, v0
	v_mov_b32_e32 v126, v0
	v_mov_b32_e32 v127, v0
	v_mov_b32_e32 v135, v134
	v_mov_b32_e32 v136, v134
	v_mov_b32_e32 v137, v134
	v_mov_b32_e32 v138, v134
	v_mov_b32_e32 v139, v134
	v_mov_b32_e32 v140, v134
	v_mov_b32_e32 v141, v134
	v_mov_b32_e32 v146, v134
	v_mov_b32_e32 v147, v134
	v_mov_b32_e32 v148, v134
	v_mov_b32_e32 v149, v134
	v_mov_b32_e32 v150, v134
	v_mov_b32_e32 v151, v134
	v_mov_b32_e32 v152, v134
	v_mov_b32_e32 v153, v134
	v_mov_b32_e32 v131, v130
	v_mov_b32_e32 v132, v130
	v_mov_b32_e32 v133, v130
	v_mov_b32_e32 v142, v130
	v_mov_b32_e32 v143, v130
	v_mov_b32_e32 v144, v130
	v_mov_b32_e32 v145, v130
	.p2alignl 6, 3212836864

.LBB0_262:
	s_and_b32 s5, s2, 7
	v_lshl_add_u32 v0, s5, 8, v201
	v_ashrrev_i32_e32 v1, 31, v0
	v_lshlrev_b64 v[0:1], 11, v[0:1]
	s_and_b32 s5, s4, 0xffffff00
	v_lshl_add_u64 v[170:171], v[160:161], 0, v[0:1]
	v_add_u32_e32 v0, s5, v175
	s_and_b32 s5, s6, 7
	v_ashrrev_i32_e32 v1, 31, v0
	s_or_b32 s5, s5, s3
	v_lshlrev_b64 v[0:1], 11, v[0:1]
	s_lshl_b32 s5, s5, 8
	v_lshl_add_u64 v[172:173], v[168:169], 0, v[0:1]
	v_add_u32_e32 v0, s5, v175
	s_lshl_b32 s7, s6, 5
	v_ashrrev_i32_e32 v1, 31, v0
	s_and_b32 s7, s7, 0xffffff00
	v_add_u32_e32 v2, s7, v175
	v_lshlrev_b64 v[0:1], 11, v[0:1]
	s_waitcnt vmcnt(0) lgkmcnt(0)
	s_barrier
	v_ashrrev_i32_e32 v3, 31, v2
	v_lshl_add_u64 v[0:1], v[154:155], 0, v[0:1]
	v_readfirstlane_b32 s10, v180
	s_mov_b32 m0, s10
	s_nop 0
	global_load_lds_dwordx4 v[0:1], off
	v_lshlrev_b64 v[2:3], 11, v[2:3]
	v_lshl_add_u64 v[4:5], v[0:1], 0, s[34:35]
	s_add_i32 s11, s10, 0x2000
	s_mov_b32 m0, s11
	s_nop 0
	global_load_lds_dwordx4 v[4:5], off
	v_lshl_add_u64 v[2:3], v[156:157], 0, v[2:3]
	s_add_i32 s11, s10, 0x4000
	s_mov_b32 m0, s11
	s_nop 0
	global_load_lds_dwordx4 v[2:3], off
	v_lshl_add_u64 v[4:5], v[2:3], 0, s[34:35]
	s_add_i32 s11, s10, 0x6000
	s_mov_b32 m0, s11
	s_nop 0
	global_load_lds_dwordx4 v[4:5], off
	s_add_i32 s11, s10, 0x8000
	v_lshl_add_u64 v[4:5], v[0:1], 0, 64
	s_mov_b32 m0, s11
	s_nop 0
	global_load_lds_dwordx4 v[4:5], off
	s_mov_b64 s[12:13], 0x40040
	v_lshl_add_u64 v[4:5], v[0:1], 0, s[12:13]
	s_add_i32 s11, s10, 0xa000
	s_mov_b32 m0, s11
	s_nop 0
	global_load_lds_dwordx4 v[4:5], off
	v_lshl_add_u64 v[4:5], v[2:3], 0, 64
	s_add_i32 s11, s10, 0xc000
	s_mov_b32 m0, s11
	s_nop 0
	global_load_lds_dwordx4 v[4:5], off
	v_lshl_add_u64 v[4:5], v[2:3], 0, s[12:13]
	s_add_i32 s11, s10, 0xe000
	s_mov_b32 m0, s11
	s_nop 0
	global_load_lds_dwordx4 v[4:5], off
	s_mov_b64 s[12:13], 0x80
	s_add_i32 s11, s10, 0x10000
	v_lshl_add_u64 v[4:5], v[0:1], 0, s[12:13]
	s_mov_b32 m0, s11
	s_nop 0
	global_load_lds_dwordx4 v[4:5], off
	s_mov_b64 s[14:15], 0x40080
	v_lshl_add_u64 v[0:1], v[0:1], 0, s[14:15]
	s_add_i32 s11, s10, 0x12000
	s_mov_b32 m0, s11
	s_nop 0
	global_load_lds_dwordx4 v[0:1], off
	v_lshl_add_u64 v[0:1], v[2:3], 0, s[12:13]
	s_add_i32 s11, s10, 0x14000
	s_mov_b32 m0, s11
	s_nop 0
	global_load_lds_dwordx4 v[0:1], off
	v_lshl_add_u64 v[0:1], v[2:3], 0, s[14:15]
	s_add_i32 s10, s10, 0x16000
	s_mov_b32 m0, s10
	s_nop 0
	global_load_lds_dwordx4 v[0:1], off
	v_mov_b32_e32 v130, 0
	v_mov_b32_e32 v134, 0
	v_mov_b32_e32 v0, 0
	s_mov_b32 s10, 0x18000
	v_mov_b32_e32 v1, v0
	v_mov_b32_e32 v2, v0
	v_mov_b32_e32 v3, v0
	v_mov_b32_e32 v4, v0
	v_mov_b32_e32 v5, v0
	v_mov_b32_e32 v6, v0
	v_mov_b32_e32 v7, v0
	v_mov_b32_e32 v8, v0
	v_mov_b32_e32 v9, v0
	v_mov_b32_e32 v10, v0
	v_mov_b32_e32 v11, v0
	v_mov_b32_e32 v12, v0
	v_mov_b32_e32 v13, v0
	v_mov_b32_e32 v14, v0
	v_mov_b32_e32 v15, v0
	v_mov_b32_e32 v16, v0
	v_mov_b32_e32 v17, v0
	v_mov_b32_e32 v18, v0
	v_mov_b32_e32 v19, v0
	v_mov_b32_e32 v20, v0
	v_mov_b32_e32 v21, v0
	v_mov_b32_e32 v22, v0
	v_mov_b32_e32 v23, v0
	v_mov_b32_e32 v24, v0
	v_mov_b32_e32 v25, v0
	v_mov_b32_e32 v26, v0
	v_mov_b32_e32 v27, v0
	v_mov_b32_e32 v28, v0
	v_mov_b32_e32 v29, v0
	v_mov_b32_e32 v30, v0
	v_mov_b32_e32 v31, v0
	v_mov_b32_e32 v32, v0
	v_mov_b32_e32 v33, v0
	v_mov_b32_e32 v34, v0
	v_mov_b32_e32 v35, v0
	v_mov_b32_e32 v36, v0
	v_mov_b32_e32 v37, v0
	v_mov_b32_e32 v38, v0
	v_mov_b32_e32 v39, v0
	v_mov_b32_e32 v40, v0
	v_mov_b32_e32 v41, v0
	v_mov_b32_e32 v42, v0
	v_mov_b32_e32 v43, v0
	v_mov_b32_e32 v44, v0
	v_mov_b32_e32 v45, v0
	v_mov_b32_e32 v46, v0
	v_mov_b32_e32 v47, v0
	v_mov_b32_e32 v48, v0
	v_mov_b32_e32 v49, v0
	v_mov_b32_e32 v50, v0
	v_mov_b32_e32 v51, v0
	v_mov_b32_e32 v52, v0
	v_mov_b32_e32 v53, v0
	v_mov_b32_e32 v54, v0
	v_mov_b32_e32 v55, v0
	v_mov_b32_e32 v56, v0
	v_mov_b32_e32 v57, v0
	v_mov_b32_e32 v58, v0
	v_mov_b32_e32 v59, v0
	v_mov_b32_e32 v60, v0
	v_mov_b32_e32 v61, v0
	v_mov_b32_e32 v62, v0
	v_mov_b32_e32 v63, v0
	v_mov_b32_e32 v64, v0
	v_mov_b32_e32 v65, v0
	v_mov_b32_e32 v66, v0
	v_mov_b32_e32 v67, v0
	v_mov_b32_e32 v68, v0
	v_mov_b32_e32 v69, v0
	v_mov_b32_e32 v70, v0
	v_mov_b32_e32 v71, v0
	v_mov_b32_e32 v72, v0
	v_mov_b32_e32 v73, v0
	v_mov_b32_e32 v74, v0
	v_mov_b32_e32 v75, v0
	v_mov_b32_e32 v76, v0
	v_mov_b32_e32 v77, v0
	v_mov_b32_e32 v78, v0
	v_mov_b32_e32 v79, v0
	v_mov_b32_e32 v80, v0
	v_mov_b32_e32 v81, v0
	v_mov_b32_e32 v82, v0
	v_mov_b32_e32 v83, v0
	v_mov_b32_e32 v84, v0
	v_mov_b32_e32 v85, v0
	v_mov_b32_e32 v86, v0
	v_mov_b32_e32 v87, v0
	v_mov_b32_e32 v88, v0
	v_mov_b32_e32 v89, v0
	v_mov_b32_e32 v90, v0
	v_mov_b32_e32 v91, v0
	v_mov_b32_e32 v92, v0
	v_mov_b32_e32 v93, v0
	v_mov_b32_e32 v94, v0
	v_mov_b32_e32 v95, v0
	v_mov_b32_e32 v96, v0
	v_mov_b32_e32 v97, v0
	v_mov_b32_e32 v98, v0
	v_mov_b32_e32 v99, v0
	v_mov_b32_e32 v100, v0
	v_mov_b32_e32 v101, v0
	v_mov_b32_e32 v102, v0
	v_mov_b32_e32 v103, v0
	v_mov_b32_e32 v104, v0
	v_mov_b32_e32 v105, v0
	v_mov_b32_e32 v106, v0
	v_mov_b32_e32 v107, v0
	v_mov_b32_e32 v108, v0
	v_mov_b32_e32 v109, v0
	v_mov_b32_e32 v110, v0
	v_mov_b32_e32 v111, v0
	v_mov_b32_e32 v112, v0
	v_mov_b32_e32 v113, v0
	v_mov_b32_e32 v114, v0
	v_mov_b32_e32 v115, v0
	v_mov_b32_e32 v116, v0
	v_mov_b32_e32 v117, v0
	v_mov_b32_e32 v118, v0
	v_mov_b32_e32 v119, v0
	v_mov_b32_e32 v120, v0
	v_mov_b32_e32 v121, v0
	v_mov_b32_e32 v122, v0
	v_mov_b32_e32 v123, v0
	v_mov_b32_e32 v124, v0
	v_mov_b32_e32 v125, v0
	v_mov_b32_e32 v126, v0
	v_mov_b32_e32 v127, v0
	v_mov_b32_e32 v135, v134
	v_mov_b32_e32 v136, v134
	v_mov_b32_e32 v137, v134
	v_mov_b32_e32 v138, v134
	v_mov_b32_e32 v139, v134
	v_mov_b32_e32 v140, v134
	v_mov_b32_e32 v141, v134
	v_mov_b32_e32 v146, v134
	v_mov_b32_e32 v147, v134
	v_mov_b32_e32 v148, v134
	v_mov_b32_e32 v149, v134
	v_mov_b32_e32 v150, v134
	v_mov_b32_e32 v151, v134
	v_mov_b32_e32 v152, v134
	v_mov_b32_e32 v153, v134
	v_mov_b32_e32 v131, v130
	v_mov_b32_e32 v132, v130
	v_mov_b32_e32 v133, v130
	v_mov_b32_e32 v142, v130
	v_mov_b32_e32 v143, v130
	v_mov_b32_e32 v144, v130
	v_mov_b32_e32 v145, v130
	.p2alignl 6, 3212836864

.LBB0_329:
	s_and_b32 s0, s31, 7
	v_lshl_add_u32 v0, s0, 8, v189
	v_ashrrev_i32_e32 v1, 31, v0
	v_lshlrev_b64 v[0:1], 11, v[0:1]
	s_and_b32 s0, s35, 0xffffff00
	v_lshl_add_u64 v[172:173], v[168:169], 0, v[0:1]
	v_add_u32_e32 v0, s0, v177
	s_and_b32 s0, s30, 7
	v_ashrrev_i32_e32 v1, 31, v0
	s_or_b32 s0, s0, s34
	v_lshlrev_b64 v[0:1], 11, v[0:1]
	s_lshl_b32 s0, s0, 8
	v_lshl_add_u64 v[174:175], v[170:171], 0, v[0:1]
	v_add_u32_e32 v0, s0, v177
	s_lshl_b32 s1, s30, 5
	v_ashrrev_i32_e32 v1, 31, v0
	s_and_b32 s1, s1, 0xffffff00
	v_lshlrev_b64 v[0:1], 11, v[0:1]
	v_add_u32_e32 v2, s1, v177
	s_waitcnt vmcnt(0) lgkmcnt(0)
	s_barrier
	v_ashrrev_i32_e32 v3, 31, v2
	v_lshl_add_u64 v[0:1], v[158:159], 0, v[0:1]
	v_readfirstlane_b32 s2, v182
	s_mov_b32 m0, s2
	s_nop 0
	global_load_lds_dwordx4 v[0:1], off
	s_mov_b64 s[26:27], 0x40000
	v_lshlrev_b64 v[2:3], 11, v[2:3]
	v_lshl_add_u64 v[4:5], v[0:1], 0, s[26:27]
	s_add_i32 s3, s2, 0x2000
	s_mov_b32 m0, s3
	s_nop 0
	global_load_lds_dwordx4 v[4:5], off
	v_lshl_add_u64 v[2:3], v[160:161], 0, v[2:3]
	s_add_i32 s3, s2, 0x4000
	s_mov_b32 m0, s3
	s_nop 0
	global_load_lds_dwordx4 v[2:3], off
	v_lshl_add_u64 v[4:5], v[2:3], 0, s[26:27]
	s_add_i32 s3, s2, 0x6000
	s_mov_b32 m0, s3
	s_nop 0
	global_load_lds_dwordx4 v[4:5], off
	s_add_i32 s3, s2, 0x8000
	v_lshl_add_u64 v[4:5], v[0:1], 0, 64
	s_mov_b32 m0, s3
	s_nop 0
	global_load_lds_dwordx4 v[4:5], off
	s_mov_b64 s[24:25], 0x40040
	v_lshl_add_u64 v[4:5], v[0:1], 0, s[24:25]
	s_add_i32 s3, s2, 0xa000
	s_mov_b32 m0, s3
	s_nop 0
	global_load_lds_dwordx4 v[4:5], off
	v_lshl_add_u64 v[4:5], v[2:3], 0, 64
	s_add_i32 s3, s2, 0xc000
	s_mov_b32 m0, s3
	s_nop 0
	global_load_lds_dwordx4 v[4:5], off
	v_lshl_add_u64 v[4:5], v[2:3], 0, s[24:25]
	s_add_i32 s3, s2, 0xe000
	s_mov_b32 m0, s3
	s_nop 0
	global_load_lds_dwordx4 v[4:5], off
	s_mov_b64 s[24:25], 0x80
	s_add_i32 s3, s2, 0x10000
	v_lshl_add_u64 v[4:5], v[0:1], 0, s[24:25]
	s_mov_b32 m0, s3
	s_nop 0
	global_load_lds_dwordx4 v[4:5], off
	s_mov_b64 s[28:29], 0x40080
	v_lshl_add_u64 v[0:1], v[0:1], 0, s[28:29]
	s_add_i32 s3, s2, 0x12000
	s_mov_b32 m0, s3
	s_nop 0
	global_load_lds_dwordx4 v[0:1], off
	v_lshl_add_u64 v[0:1], v[2:3], 0, s[24:25]
	s_add_i32 s3, s2, 0x14000
	s_mov_b32 m0, s3
	s_nop 0
	global_load_lds_dwordx4 v[0:1], off
	v_lshl_add_u64 v[0:1], v[2:3], 0, s[28:29]
	s_add_i32 s2, s2, 0x16000
	s_mov_b32 m0, s2
	s_nop 0
	global_load_lds_dwordx4 v[0:1], off
	v_mov_b32_e32 v130, 0
	v_mov_b32_e32 v134, 0
	v_mov_b32_e32 v0, 0
	s_mov_b32 s2, 0x18000
	v_mov_b32_e32 v1, v0
	v_mov_b32_e32 v2, v0
	v_mov_b32_e32 v3, v0
	v_mov_b32_e32 v4, v0
	v_mov_b32_e32 v5, v0
	v_mov_b32_e32 v6, v0
	v_mov_b32_e32 v7, v0
	v_mov_b32_e32 v8, v0
	v_mov_b32_e32 v9, v0
	v_mov_b32_e32 v10, v0
	v_mov_b32_e32 v11, v0
	v_mov_b32_e32 v12, v0
	v_mov_b32_e32 v13, v0
	v_mov_b32_e32 v14, v0
	v_mov_b32_e32 v15, v0
	v_mov_b32_e32 v16, v0
	v_mov_b32_e32 v17, v0
	v_mov_b32_e32 v18, v0
	v_mov_b32_e32 v19, v0
	v_mov_b32_e32 v20, v0
	v_mov_b32_e32 v21, v0
	v_mov_b32_e32 v22, v0
	v_mov_b32_e32 v23, v0
	v_mov_b32_e32 v24, v0
	v_mov_b32_e32 v25, v0
	v_mov_b32_e32 v26, v0
	v_mov_b32_e32 v27, v0
	v_mov_b32_e32 v28, v0
	v_mov_b32_e32 v29, v0
	v_mov_b32_e32 v30, v0
	v_mov_b32_e32 v31, v0
	v_mov_b32_e32 v32, v0
	v_mov_b32_e32 v33, v0
	v_mov_b32_e32 v34, v0
	v_mov_b32_e32 v35, v0
	v_mov_b32_e32 v36, v0
	v_mov_b32_e32 v37, v0
	v_mov_b32_e32 v38, v0
	v_mov_b32_e32 v39, v0
	v_mov_b32_e32 v40, v0
	v_mov_b32_e32 v41, v0
	v_mov_b32_e32 v42, v0
	v_mov_b32_e32 v43, v0
	v_mov_b32_e32 v44, v0
	v_mov_b32_e32 v45, v0
	v_mov_b32_e32 v46, v0
	v_mov_b32_e32 v47, v0
	v_mov_b32_e32 v48, v0
	v_mov_b32_e32 v49, v0
	v_mov_b32_e32 v50, v0
	v_mov_b32_e32 v51, v0
	v_mov_b32_e32 v52, v0
	v_mov_b32_e32 v53, v0
	v_mov_b32_e32 v54, v0
	v_mov_b32_e32 v55, v0
	v_mov_b32_e32 v56, v0
	v_mov_b32_e32 v57, v0
	v_mov_b32_e32 v58, v0
	v_mov_b32_e32 v59, v0
	v_mov_b32_e32 v60, v0
	v_mov_b32_e32 v61, v0
	v_mov_b32_e32 v62, v0
	v_mov_b32_e32 v63, v0
	v_mov_b32_e32 v64, v0
	v_mov_b32_e32 v65, v0
	v_mov_b32_e32 v66, v0
	v_mov_b32_e32 v67, v0
	v_mov_b32_e32 v68, v0
	v_mov_b32_e32 v69, v0
	v_mov_b32_e32 v70, v0
	v_mov_b32_e32 v71, v0
	v_mov_b32_e32 v72, v0
	v_mov_b32_e32 v73, v0
	v_mov_b32_e32 v74, v0
	v_mov_b32_e32 v75, v0
	v_mov_b32_e32 v76, v0
	v_mov_b32_e32 v77, v0
	v_mov_b32_e32 v78, v0
	v_mov_b32_e32 v79, v0
	v_mov_b32_e32 v80, v0
	v_mov_b32_e32 v81, v0
	v_mov_b32_e32 v82, v0
	v_mov_b32_e32 v83, v0
	v_mov_b32_e32 v84, v0
	v_mov_b32_e32 v85, v0
	v_mov_b32_e32 v86, v0
	v_mov_b32_e32 v87, v0
	v_mov_b32_e32 v88, v0
	v_mov_b32_e32 v89, v0
	v_mov_b32_e32 v90, v0
	v_mov_b32_e32 v91, v0
	v_mov_b32_e32 v92, v0
	v_mov_b32_e32 v93, v0
	v_mov_b32_e32 v94, v0
	v_mov_b32_e32 v95, v0
	v_mov_b32_e32 v96, v0
	v_mov_b32_e32 v97, v0
	v_mov_b32_e32 v98, v0
	v_mov_b32_e32 v99, v0
	v_mov_b32_e32 v100, v0
	v_mov_b32_e32 v101, v0
	v_mov_b32_e32 v102, v0
	v_mov_b32_e32 v103, v0
	v_mov_b32_e32 v104, v0
	v_mov_b32_e32 v105, v0
	v_mov_b32_e32 v106, v0
	v_mov_b32_e32 v107, v0
	v_mov_b32_e32 v108, v0
	v_mov_b32_e32 v109, v0
	v_mov_b32_e32 v110, v0
	v_mov_b32_e32 v111, v0
	v_mov_b32_e32 v112, v0
	v_mov_b32_e32 v113, v0
	v_mov_b32_e32 v114, v0
	v_mov_b32_e32 v115, v0
	v_mov_b32_e32 v116, v0
	v_mov_b32_e32 v117, v0
	v_mov_b32_e32 v118, v0
	v_mov_b32_e32 v119, v0
	v_mov_b32_e32 v120, v0
	v_mov_b32_e32 v121, v0
	v_mov_b32_e32 v122, v0
	v_mov_b32_e32 v123, v0
	v_mov_b32_e32 v124, v0
	v_mov_b32_e32 v125, v0
	v_mov_b32_e32 v126, v0
	v_mov_b32_e32 v127, v0
	v_mov_b32_e32 v135, v134
	v_mov_b32_e32 v136, v134
	v_mov_b32_e32 v137, v134
	v_mov_b32_e32 v138, v134
	v_mov_b32_e32 v139, v134
	v_mov_b32_e32 v140, v134
	v_mov_b32_e32 v141, v134
	v_mov_b32_e32 v146, v134
	v_mov_b32_e32 v147, v134
	v_mov_b32_e32 v148, v134
	v_mov_b32_e32 v149, v134
	v_mov_b32_e32 v150, v134
	v_mov_b32_e32 v151, v134
	v_mov_b32_e32 v152, v134
	v_mov_b32_e32 v153, v134
	v_mov_b32_e32 v131, v130
	v_mov_b32_e32 v132, v130
	v_mov_b32_e32 v133, v130
	v_mov_b32_e32 v142, v130
	v_mov_b32_e32 v143, v130
	v_mov_b32_e32 v144, v130
	v_mov_b32_e32 v145, v130
	.p2alignl 6, 3212836864

.LBB0_1034:
	s_lshl_b32 s12, s12, 7
	s_add_i32 s12, s13, s12
	v_add_u32_e32 v0, s12, v184
	v_ashrrev_i32_e32 v1, 31, v0
	s_lshl_b32 s12, s19, 7
	v_lshlrev_b64 v[2:3], 11, v[0:1]
	s_and_b32 s14, s12, 0x380
	v_readlane_b32 s12, v252, 12
	v_lshl_add_u64 v[2:3], s[10:11], 0, v[2:3]
	v_readlane_b32 s13, v252, 13
	s_lshl_b32 s12, s14, 1
	v_mov_b32_e32 v161, v129
	v_lshl_add_u64 v[2:3], v[2:3], 0, s[12:13]
	v_lshl_add_u64 v[2:3], v[2:3], 0, v[128:129]
	global_load_dwordx4 v[120:123], v[2:3], off
	global_load_dwordx4 v[124:127], v[2:3], off offset:32
	global_load_dwordx4 v[130:133], v[2:3], off offset:128
	global_load_dwordx4 v[134:137], v[2:3], off offset:160
	global_load_dwordx4 v[138:141], v[2:3], off offset:64
	global_load_dwordx4 v[142:145], v[2:3], off offset:96
	global_load_dwordx4 v[146:149], v[2:3], off offset:192
	global_load_dwordx4 v[150:153], v[2:3], off offset:224
	v_add_u32_e32 v2, s15, v182
	v_ashrrev_i32_e32 v3, 31, v2
	v_lshlrev_b64 v[2:3], 11, v[2:3]
	v_lshl_add_u64 v[4:5], s[4:5], 0, v[2:3]
	v_lshl_add_u64 v[4:5], v[4:5], 0, s[12:13]
	v_lshl_add_u64 v[4:5], v[4:5], 0, v[160:161]
	s_mov_b32 s12, 0x8000
	v_add_co_u32_e32 v6, vcc, s12, v4
	s_waitcnt vmcnt(63) expcnt(7) lgkmcnt(15)
	s_barrier
	v_addc_co_u32_e32 v7, vcc, 0, v5, vcc
	global_load_dwordx4 v[32:35], v[4:5], off
	global_load_dwordx4 v[36:39], v[6:7], off
	s_and_b32 s12, s19, 7
	v_lshl_or_b32 v2, s12, 8, v2
	v_mov_b32_e32 v40, 0
	v_lshl_add_u64 v[174:175], v[156:157], 0, v[2:3]
	s_mov_b32 s23, s13
	s_lshr_b32 s15, s18, 5
	s_mov_b32 s20, 0
	v_mov_b32_e32 v45, 0xf149f2ca
	v_mov_b32_e32 v47, 0xf149f2ca
	v_lshlrev_b64 v[172:173], 10, v[0:1]
	v_mov_b64_e32 v[42:43], v[174:175]
	v_mov_b32_e32 v41, v40
	s_waitcnt vmcnt(1)
	ds_write_b128 v185, v[32:35]
	s_waitcnt vmcnt(0)
	ds_write_b128 v185, v[36:39] offset:4352
	s_waitcnt lgkmcnt(0)
	s_barrier
	.p2alignl 6, 3212836864

.LBB0_1042:
	s_mov_b64 s[2:3], 0x10000
	s_add_i32 s12, s12, 1
	v_lshl_add_u64 v[174:175], v[174:175], 0, s[2:3]
	s_add_i32 s2, s13, s12
	v_lshl_add_u64 v[178:179], v[178:179], 0, 64
	s_cmp_eq_u32 s2, 1
	v_lshl_add_u64 v[180:181], v[180:181], 0, 64
	s_waitcnt lgkmcnt(0)
	s_barrier
	s_cbranch_scc1 .LBB0_1029
	.p2alignl 6, 3212836864

.LBB0_1101:
	s_and_b32 s3, s0, 7
	v_lshl_add_u32 v0, s3, 8, v201
	v_ashrrev_i32_e32 v1, 31, v0
	v_lshlrev_b64 v[0:1], 11, v[0:1]
	s_and_b32 s3, s2, 0xffffff00
	v_lshl_add_u64 v[170:171], v[160:161], 0, v[0:1]
	v_add_u32_e32 v0, s3, v175
	s_and_b32 s3, s4, 7
	v_ashrrev_i32_e32 v1, 31, v0
	s_or_b32 s3, s3, s1
	v_lshlrev_b64 v[0:1], 11, v[0:1]
	s_lshl_b32 s3, s3, 8
	v_lshl_add_u64 v[172:173], v[168:169], 0, v[0:1]
	v_add_u32_e32 v0, s3, v175
	s_lshl_b32 s5, s4, 5
	v_ashrrev_i32_e32 v1, 31, v0
	s_and_b32 s5, s5, 0xffffff00
	v_add_u32_e32 v2, s5, v175
	v_lshlrev_b64 v[0:1], 11, v[0:1]
	s_waitcnt vmcnt(0) lgkmcnt(0)
	s_barrier
	v_ashrrev_i32_e32 v3, 31, v2
	v_lshl_add_u64 v[0:1], v[154:155], 0, v[0:1]
	v_readfirstlane_b32 s6, v180
	s_mov_b32 m0, s6
	s_nop 0
	global_load_lds_dwordx4 v[0:1], off
	v_lshlrev_b64 v[2:3], 11, v[2:3]
	v_lshl_add_u64 v[4:5], v[0:1], 0, s[34:35]
	s_add_i32 s7, s6, 0x2000
	s_mov_b32 m0, s7
	s_nop 0
	global_load_lds_dwordx4 v[4:5], off
	v_lshl_add_u64 v[2:3], v[156:157], 0, v[2:3]
	s_add_i32 s7, s6, 0x4000
	s_mov_b32 m0, s7
	s_nop 0
	global_load_lds_dwordx4 v[2:3], off
	v_lshl_add_u64 v[4:5], v[2:3], 0, s[34:35]
	s_add_i32 s7, s6, 0x6000
	s_mov_b32 m0, s7
	s_nop 0
	global_load_lds_dwordx4 v[4:5], off
	s_add_i32 s7, s6, 0x8000
	v_lshl_add_u64 v[4:5], v[0:1], 0, 64
	s_mov_b32 m0, s7
	s_nop 0
	global_load_lds_dwordx4 v[4:5], off
	s_mov_b64 s[10:11], 0x40040
	v_lshl_add_u64 v[4:5], v[0:1], 0, s[10:11]
	s_add_i32 s7, s6, 0xa000
	s_mov_b32 m0, s7
	s_nop 0
	global_load_lds_dwordx4 v[4:5], off
	v_lshl_add_u64 v[4:5], v[2:3], 0, 64
	s_add_i32 s7, s6, 0xc000
	s_mov_b32 m0, s7
	s_nop 0
	global_load_lds_dwordx4 v[4:5], off
	v_lshl_add_u64 v[4:5], v[2:3], 0, s[10:11]
	s_add_i32 s7, s6, 0xe000
	s_mov_b32 m0, s7
	s_nop 0
	global_load_lds_dwordx4 v[4:5], off
	s_mov_b64 s[10:11], 0x80
	s_add_i32 s7, s6, 0x10000
	v_lshl_add_u64 v[4:5], v[0:1], 0, s[10:11]
	s_mov_b32 m0, s7
	s_nop 0
	global_load_lds_dwordx4 v[4:5], off
	s_mov_b64 s[12:13], 0x40080
	v_lshl_add_u64 v[0:1], v[0:1], 0, s[12:13]
	s_add_i32 s7, s6, 0x12000
	s_mov_b32 m0, s7
	s_nop 0
	global_load_lds_dwordx4 v[0:1], off
	v_lshl_add_u64 v[0:1], v[2:3], 0, s[10:11]
	s_add_i32 s7, s6, 0x14000
	s_mov_b32 m0, s7
	s_nop 0
	global_load_lds_dwordx4 v[0:1], off
	v_lshl_add_u64 v[0:1], v[2:3], 0, s[12:13]
	s_add_i32 s6, s6, 0x16000
	s_mov_b32 m0, s6
	s_nop 0
	global_load_lds_dwordx4 v[0:1], off
	v_mov_b32_e32 v130, 0
	v_mov_b32_e32 v134, 0
	v_mov_b32_e32 v0, 0
	s_mov_b32 s6, 0x18000
	v_mov_b32_e32 v1, v0
	v_mov_b32_e32 v2, v0
	v_mov_b32_e32 v3, v0
	v_mov_b32_e32 v4, v0
	v_mov_b32_e32 v5, v0
	v_mov_b32_e32 v6, v0
	v_mov_b32_e32 v7, v0
	v_mov_b32_e32 v8, v0
	v_mov_b32_e32 v9, v0
	v_mov_b32_e32 v10, v0
	v_mov_b32_e32 v11, v0
	v_mov_b32_e32 v12, v0
	v_mov_b32_e32 v13, v0
	v_mov_b32_e32 v14, v0
	v_mov_b32_e32 v15, v0
	v_mov_b32_e32 v16, v0
	v_mov_b32_e32 v17, v0
	v_mov_b32_e32 v18, v0
	v_mov_b32_e32 v19, v0
	v_mov_b32_e32 v20, v0
	v_mov_b32_e32 v21, v0
	v_mov_b32_e32 v22, v0
	v_mov_b32_e32 v23, v0
	v_mov_b32_e32 v24, v0
	v_mov_b32_e32 v25, v0
	v_mov_b32_e32 v26, v0
	v_mov_b32_e32 v27, v0
	v_mov_b32_e32 v28, v0
	v_mov_b32_e32 v29, v0
	v_mov_b32_e32 v30, v0
	v_mov_b32_e32 v31, v0
	v_mov_b32_e32 v32, v0
	v_mov_b32_e32 v33, v0
	v_mov_b32_e32 v34, v0
	v_mov_b32_e32 v35, v0
	v_mov_b32_e32 v36, v0
	v_mov_b32_e32 v37, v0
	v_mov_b32_e32 v38, v0
	v_mov_b32_e32 v39, v0
	v_mov_b32_e32 v40, v0
	v_mov_b32_e32 v41, v0
	v_mov_b32_e32 v42, v0
	v_mov_b32_e32 v43, v0
	v_mov_b32_e32 v44, v0
	v_mov_b32_e32 v45, v0
	v_mov_b32_e32 v46, v0
	v_mov_b32_e32 v47, v0
	v_mov_b32_e32 v48, v0
	v_mov_b32_e32 v49, v0
	v_mov_b32_e32 v50, v0
	v_mov_b32_e32 v51, v0
	v_mov_b32_e32 v52, v0
	v_mov_b32_e32 v53, v0
	v_mov_b32_e32 v54, v0
	v_mov_b32_e32 v55, v0
	v_mov_b32_e32 v56, v0
	v_mov_b32_e32 v57, v0
	v_mov_b32_e32 v58, v0
	v_mov_b32_e32 v59, v0
	v_mov_b32_e32 v60, v0
	v_mov_b32_e32 v61, v0
	v_mov_b32_e32 v62, v0
	v_mov_b32_e32 v63, v0
	v_mov_b32_e32 v64, v0
	v_mov_b32_e32 v65, v0
	v_mov_b32_e32 v66, v0
	v_mov_b32_e32 v67, v0
	v_mov_b32_e32 v68, v0
	v_mov_b32_e32 v69, v0
	v_mov_b32_e32 v70, v0
	v_mov_b32_e32 v71, v0
	v_mov_b32_e32 v72, v0
	v_mov_b32_e32 v73, v0
	v_mov_b32_e32 v74, v0
	v_mov_b32_e32 v75, v0
	v_mov_b32_e32 v76, v0
	v_mov_b32_e32 v77, v0
	v_mov_b32_e32 v78, v0
	v_mov_b32_e32 v79, v0
	v_mov_b32_e32 v80, v0
	v_mov_b32_e32 v81, v0
	v_mov_b32_e32 v82, v0
	v_mov_b32_e32 v83, v0
	v_mov_b32_e32 v84, v0
	v_mov_b32_e32 v85, v0
	v_mov_b32_e32 v86, v0
	v_mov_b32_e32 v87, v0
	v_mov_b32_e32 v88, v0
	v_mov_b32_e32 v89, v0
	v_mov_b32_e32 v90, v0
	v_mov_b32_e32 v91, v0
	v_mov_b32_e32 v92, v0
	v_mov_b32_e32 v93, v0
	v_mov_b32_e32 v94, v0
	v_mov_b32_e32 v95, v0
	v_mov_b32_e32 v96, v0
	v_mov_b32_e32 v97, v0
	v_mov_b32_e32 v98, v0
	v_mov_b32_e32 v99, v0
	v_mov_b32_e32 v100, v0
	v_mov_b32_e32 v101, v0
	v_mov_b32_e32 v102, v0
	v_mov_b32_e32 v103, v0
	v_mov_b32_e32 v104, v0
	v_mov_b32_e32 v105, v0
	v_mov_b32_e32 v106, v0
	v_mov_b32_e32 v107, v0
	v_mov_b32_e32 v108, v0
	v_mov_b32_e32 v109, v0
	v_mov_b32_e32 v110, v0
	v_mov_b32_e32 v111, v0
	v_mov_b32_e32 v112, v0
	v_mov_b32_e32 v113, v0
	v_mov_b32_e32 v114, v0
	v_mov_b32_e32 v115, v0
	v_mov_b32_e32 v116, v0
	v_mov_b32_e32 v117, v0
	v_mov_b32_e32 v118, v0
	v_mov_b32_e32 v119, v0
	v_mov_b32_e32 v120, v0
	v_mov_b32_e32 v121, v0
	v_mov_b32_e32 v122, v0
	v_mov_b32_e32 v123, v0
	v_mov_b32_e32 v124, v0
	v_mov_b32_e32 v125, v0
	v_mov_b32_e32 v126, v0
	v_mov_b32_e32 v127, v0
	v_mov_b32_e32 v135, v134
	v_mov_b32_e32 v136, v134
	v_mov_b32_e32 v137, v134
	v_mov_b32_e32 v138, v134
	v_mov_b32_e32 v139, v134
	v_mov_b32_e32 v140, v134
	v_mov_b32_e32 v141, v134
	v_mov_b32_e32 v146, v134
	v_mov_b32_e32 v147, v134
	v_mov_b32_e32 v148, v134
	v_mov_b32_e32 v149, v134
	v_mov_b32_e32 v150, v134
	v_mov_b32_e32 v151, v134
	v_mov_b32_e32 v152, v134
	v_mov_b32_e32 v153, v134
	v_mov_b32_e32 v131, v130
	v_mov_b32_e32 v132, v130
	v_mov_b32_e32 v133, v130
	v_mov_b32_e32 v142, v130
	v_mov_b32_e32 v143, v130
	v_mov_b32_e32 v144, v130
	v_mov_b32_e32 v145, v130
	.p2alignl 6, 3212836864

.LBB0_1160:
	s_and_b32 s0, s31, 7
	s_nop 0
	v_lshl_add_u32 v0, s0, 8, v238
	v_ashrrev_i32_e32 v1, 31, v0
	v_lshlrev_b64 v[0:1], 11, v[0:1]
	s_and_b32 s0, s35, 0xffffff00
	v_lshl_add_u64 v[172:173], v[168:169], 0, v[0:1]
	v_add_u32_e32 v0, s0, v198
	s_and_b32 s0, s30, 7
	v_ashrrev_i32_e32 v1, 31, v0
	s_or_b32 s0, s0, s34
	v_lshlrev_b64 v[0:1], 11, v[0:1]
	s_lshl_b32 s0, s0, 8
	v_lshl_add_u64 v[174:175], v[170:171], 0, v[0:1]
	v_add_u32_e32 v0, s0, v198
	s_lshl_b32 s24, s30, 5
	v_ashrrev_i32_e32 v1, 31, v0
	s_and_b32 s1, s24, 0xffffff00
	v_lshlrev_b64 v[0:1], 11, v[0:1]
	v_add_u32_e32 v2, s1, v198
	s_waitcnt vmcnt(0) lgkmcnt(0)
	s_barrier
	v_ashrrev_i32_e32 v3, 31, v2
	v_lshl_add_u64 v[0:1], v[154:155], 0, v[0:1]
	v_readfirstlane_b32 s20, v203
	s_mov_b32 m0, s20
	s_nop 0
	global_load_lds_dwordx4 v[0:1], off
	s_mov_b64 s[26:27], 0x40000
	v_lshlrev_b64 v[2:3], 11, v[2:3]
	v_lshl_add_u64 v[4:5], v[0:1], 0, s[26:27]
	s_add_i32 s21, s20, 0x2000
	s_mov_b32 m0, s21
	s_nop 0
	global_load_lds_dwordx4 v[4:5], off
	v_lshl_add_u64 v[2:3], v[156:157], 0, v[2:3]
	s_add_i32 s21, s20, 0x4000
	s_mov_b32 m0, s21
	s_nop 0
	global_load_lds_dwordx4 v[2:3], off
	v_lshl_add_u64 v[4:5], v[2:3], 0, s[26:27]
	s_add_i32 s21, s20, 0x6000
	s_mov_b32 m0, s21
	s_nop 0
	global_load_lds_dwordx4 v[4:5], off
	s_add_i32 s21, s20, 0x8000
	v_lshl_add_u64 v[4:5], v[0:1], 0, 64
	s_mov_b32 m0, s21
	s_nop 0
	global_load_lds_dwordx4 v[4:5], off
	s_mov_b64 s[22:23], 0x40040
	v_lshl_add_u64 v[4:5], v[0:1], 0, s[22:23]
	s_add_i32 s21, s20, 0xa000
	s_mov_b32 m0, s21
	s_nop 0
	global_load_lds_dwordx4 v[4:5], off
	v_lshl_add_u64 v[4:5], v[2:3], 0, 64
	s_add_i32 s21, s20, 0xc000
	s_mov_b32 m0, s21
	s_nop 0
	global_load_lds_dwordx4 v[4:5], off
	v_lshl_add_u64 v[4:5], v[2:3], 0, s[22:23]
	s_add_i32 s21, s20, 0xe000
	s_mov_b32 m0, s21
	s_nop 0
	global_load_lds_dwordx4 v[4:5], off
	s_mov_b64 s[22:23], 0x80
	s_add_i32 s21, s20, 0x10000
	v_lshl_add_u64 v[4:5], v[0:1], 0, s[22:23]
	s_mov_b32 m0, s21
	s_nop 0
	global_load_lds_dwordx4 v[4:5], off
	s_mov_b64 s[28:29], 0x40080
	v_lshl_add_u64 v[0:1], v[0:1], 0, s[28:29]
	s_add_i32 s21, s20, 0x12000
	s_mov_b32 m0, s21
	s_nop 0
	global_load_lds_dwordx4 v[0:1], off
	v_lshl_add_u64 v[0:1], v[2:3], 0, s[22:23]
	s_add_i32 s21, s20, 0x14000
	s_mov_b32 m0, s21
	s_nop 0
	global_load_lds_dwordx4 v[0:1], off
	v_lshl_add_u64 v[0:1], v[2:3], 0, s[28:29]
	s_add_i32 s20, s20, 0x16000
	s_mov_b32 m0, s20
	s_nop 0
	global_load_lds_dwordx4 v[0:1], off
	v_mov_b32_e32 v130, 0
	v_mov_b32_e32 v134, 0
	v_mov_b32_e32 v0, 0
	s_mov_b32 s20, 0x18000
	v_mov_b32_e32 v1, v0
	v_mov_b32_e32 v2, v0
	v_mov_b32_e32 v3, v0
	v_mov_b32_e32 v4, v0
	v_mov_b32_e32 v5, v0
	v_mov_b32_e32 v6, v0
	v_mov_b32_e32 v7, v0
	v_mov_b32_e32 v8, v0
	v_mov_b32_e32 v9, v0
	v_mov_b32_e32 v10, v0
	v_mov_b32_e32 v11, v0
	v_mov_b32_e32 v12, v0
	v_mov_b32_e32 v13, v0
	v_mov_b32_e32 v14, v0
	v_mov_b32_e32 v15, v0
	v_mov_b32_e32 v16, v0
	v_mov_b32_e32 v17, v0
	v_mov_b32_e32 v18, v0
	v_mov_b32_e32 v19, v0
	v_mov_b32_e32 v20, v0
	v_mov_b32_e32 v21, v0
	v_mov_b32_e32 v22, v0
	v_mov_b32_e32 v23, v0
	v_mov_b32_e32 v24, v0
	v_mov_b32_e32 v25, v0
	v_mov_b32_e32 v26, v0
	v_mov_b32_e32 v27, v0
	v_mov_b32_e32 v28, v0
	v_mov_b32_e32 v29, v0
	v_mov_b32_e32 v30, v0
	v_mov_b32_e32 v31, v0
	v_mov_b32_e32 v32, v0
	v_mov_b32_e32 v33, v0
	v_mov_b32_e32 v34, v0
	v_mov_b32_e32 v35, v0
	v_mov_b32_e32 v36, v0
	v_mov_b32_e32 v37, v0
	v_mov_b32_e32 v38, v0
	v_mov_b32_e32 v39, v0
	v_mov_b32_e32 v40, v0
	v_mov_b32_e32 v41, v0
	v_mov_b32_e32 v42, v0
	v_mov_b32_e32 v43, v0
	v_mov_b32_e32 v44, v0
	v_mov_b32_e32 v45, v0
	v_mov_b32_e32 v46, v0
	v_mov_b32_e32 v47, v0
	v_mov_b32_e32 v48, v0
	v_mov_b32_e32 v49, v0
	v_mov_b32_e32 v50, v0
	v_mov_b32_e32 v51, v0
	v_mov_b32_e32 v52, v0
	v_mov_b32_e32 v53, v0
	v_mov_b32_e32 v54, v0
	v_mov_b32_e32 v55, v0
	v_mov_b32_e32 v56, v0
	v_mov_b32_e32 v57, v0
	v_mov_b32_e32 v58, v0
	v_mov_b32_e32 v59, v0
	v_mov_b32_e32 v60, v0
	v_mov_b32_e32 v61, v0
	v_mov_b32_e32 v62, v0
	v_mov_b32_e32 v63, v0
	v_mov_b32_e32 v64, v0
	v_mov_b32_e32 v65, v0
	v_mov_b32_e32 v66, v0
	v_mov_b32_e32 v67, v0
	v_mov_b32_e32 v68, v0
	v_mov_b32_e32 v69, v0
	v_mov_b32_e32 v70, v0
	v_mov_b32_e32 v71, v0
	v_mov_b32_e32 v72, v0
	v_mov_b32_e32 v73, v0
	v_mov_b32_e32 v74, v0
	v_mov_b32_e32 v75, v0
	v_mov_b32_e32 v76, v0
	v_mov_b32_e32 v77, v0
	v_mov_b32_e32 v78, v0
	v_mov_b32_e32 v79, v0
	v_mov_b32_e32 v80, v0
	v_mov_b32_e32 v81, v0
	v_mov_b32_e32 v82, v0
	v_mov_b32_e32 v83, v0
	v_mov_b32_e32 v84, v0
	v_mov_b32_e32 v85, v0
	v_mov_b32_e32 v86, v0
	v_mov_b32_e32 v87, v0
	v_mov_b32_e32 v88, v0
	v_mov_b32_e32 v89, v0
	v_mov_b32_e32 v90, v0
	v_mov_b32_e32 v91, v0
	v_mov_b32_e32 v92, v0
	v_mov_b32_e32 v93, v0
	v_mov_b32_e32 v94, v0
	v_mov_b32_e32 v95, v0
	v_mov_b32_e32 v96, v0
	v_mov_b32_e32 v97, v0
	v_mov_b32_e32 v98, v0
	v_mov_b32_e32 v99, v0
	v_mov_b32_e32 v100, v0
	v_mov_b32_e32 v101, v0
	v_mov_b32_e32 v102, v0
	v_mov_b32_e32 v103, v0
	v_mov_b32_e32 v104, v0
	v_mov_b32_e32 v105, v0
	v_mov_b32_e32 v106, v0
	v_mov_b32_e32 v107, v0
	v_mov_b32_e32 v108, v0
	v_mov_b32_e32 v109, v0
	v_mov_b32_e32 v110, v0
	v_mov_b32_e32 v111, v0
	v_mov_b32_e32 v112, v0
	v_mov_b32_e32 v113, v0
	v_mov_b32_e32 v114, v0
	v_mov_b32_e32 v115, v0
	v_mov_b32_e32 v116, v0
	v_mov_b32_e32 v117, v0
	v_mov_b32_e32 v118, v0
	v_mov_b32_e32 v119, v0
	v_mov_b32_e32 v120, v0
	v_mov_b32_e32 v121, v0
	v_mov_b32_e32 v122, v0
	v_mov_b32_e32 v123, v0
	v_mov_b32_e32 v124, v0
	v_mov_b32_e32 v125, v0
	v_mov_b32_e32 v126, v0
	v_mov_b32_e32 v127, v0
	v_mov_b32_e32 v135, v134
	v_mov_b32_e32 v136, v134
	v_mov_b32_e32 v137, v134
	v_mov_b32_e32 v138, v134
	v_mov_b32_e32 v139, v134
	v_mov_b32_e32 v140, v134
	v_mov_b32_e32 v141, v134
	v_mov_b32_e32 v146, v134
	v_mov_b32_e32 v147, v134
	v_mov_b32_e32 v148, v134
	v_mov_b32_e32 v149, v134
	v_mov_b32_e32 v150, v134
	v_mov_b32_e32 v151, v134
	v_mov_b32_e32 v152, v134
	v_mov_b32_e32 v153, v134
	v_mov_b32_e32 v131, v130
	v_mov_b32_e32 v132, v130
	v_mov_b32_e32 v133, v130
	v_mov_b32_e32 v142, v130
	v_mov_b32_e32 v143, v130
	v_mov_b32_e32 v144, v130
	v_mov_b32_e32 v145, v130
	.p2alignl 6, 3212836864

.LBB0_1978:
	s_ashr_i32 s6, s16, 3
	s_and_b32 s7, s16, 7
	s_lshl_b32 s17, s6, 7
	s_lshl_b32 s4, s7, 8
	v_readlane_b32 s12, v252, 45
	v_readlane_b32 s13, v252, 46
	s_add_u32 s12, s12, s4
	s_addc_u32 s13, s13, 0
	s_lshl_b32 s4, s17, 11
	s_add_u32 s12, s12, s4
	s_addc_u32 s13, s13, 0
	v_lshl_add_u32 v95, v234, 11, v72
	global_load_dwordx4 v[96:99], v95, s[12:13]
	s_add_u32 s12, s12, 0x8000
	s_addc_u32 s13, s13, 0
	global_load_dwordx4 v[100:103], v95, s[12:13]
	s_add_u32 s12, s12, 0x8000
	s_addc_u32 s13, s13, 0
	global_load_dwordx4 v[104:107], v95, s[12:13]
	s_add_u32 s12, s12, 0x8000
	s_addc_u32 s13, s13, 0
	global_load_dwordx4 v[108:111], v95, s[12:13]
	s_add_u32 s12, s12, 0x8000
	s_addc_u32 s13, s13, 0
	global_load_dwordx4 v[112:115], v95, s[12:13]
	s_add_u32 s12, s12, 0x8000
	s_addc_u32 s13, s13, 0
	global_load_dwordx4 v[116:119], v95, s[12:13]
	s_add_u32 s12, s12, 0x8000
	s_addc_u32 s13, s13, 0
	global_load_dwordx4 v[120:123], v95, s[12:13]
	s_add_u32 s12, s12, 0x8000
	s_addc_u32 s13, s13, 0
	global_load_dwordx4 v[124:127], v95, s[12:13]
	v_ashrrev_i32_e32 v0, 6, v65
	v_lshl_add_u32 v74, s7, 2, v0
	s_ashr_i32 s7, s6, 31
	v_lshlrev_b32_e32 v0, 6, v74
	s_lshl_b64 s[4:5], s[6:7], 11
	v_ashrrev_i32_e32 v1, 31, v0
	v_lshl_add_u64 v[0:1], s[4:5], 0, v[0:1]
	v_or_b32_e32 v0, v0, v64
	v_lshlrev_b64 v[0:1], 8, v[0:1]
	v_lshl_add_u64 v[0:1], v[66:67], 0, v[0:1]
	s_movk_i32 s11, 0x2000
	v_add_co_u32_e64 v2, s[4:5], s11, v0
	s_waitcnt lgkmcnt(0)
	s_nop 0
	v_addc_co_u32_e64 v3, s[4:5], 0, v1, s[4:5]
	s_load_dwordx2 s[100:101], s[60:61], 0xe8
	v_readfirstlane_b32 s4, v74
	v_lshlrev_b32_e32 v84, 3, v221
	s_lshl_b32 s5, s6, 15
	s_waitcnt lgkmcnt(0)
	s_add_u32 s100, s100, s5
	s_addc_u32 s101, s101, 0
	s_lshl_b32 s4, s4, 9
	s_add_u32 s100, s100, s4
	s_addc_u32 s101, s101, 0
	s_add_u32 s100, s100, 0xd08000
	s_addc_u32 s101, s101, 0
	global_load_dwordx2 v[80:81], v84, s[100:101]
	s_add_u32 s100, s100, 0x4000
	s_addc_u32 s101, s101, 0
	global_load_dwordx2 v[82:83], v84, s[100:101]
	global_load_dwordx4 v[24:27], v[0:1], off
	global_load_dwordx4 v[28:31], v[0:1], off offset:32
	global_load_dwordx4 v[32:35], v[0:1], off offset:64
	global_load_dwordx4 v[36:39], v[0:1], off offset:96
	global_load_dwordx4 v[40:43], v[2:3], off
	global_load_dwordx4 v[44:47], v[2:3], off offset:32
	global_load_dwordx4 v[48:51], v[2:3], off offset:64
	global_load_dwordx4 v[52:55], v[2:3], off offset:96
	global_load_dwordx4 v[56:59], v[0:1], off offset:128
	global_load_dwordx4 v[60:63], v[2:3], off offset:128
	global_load_dwordx4 v[20:23], v[0:1], off offset:160
	global_load_dwordx4 v[12:15], v[0:1], off offset:192
	global_load_dwordx4 v[4:7], v[0:1], off offset:224
	global_load_dwordx4 v[16:19], v[2:3], off offset:160
	global_load_dwordx4 v[8:11], v[2:3], off offset:192
	s_nop 0
	global_load_dwordx4 v[0:3], v[2:3], off offset:224
	s_barrier
	s_waitcnt vmcnt(25)
	ds_write_b16 v235, v96
	ds_write_b16_d16_hi v235, v96 offset:272
	ds_write_b16 v235, v97 offset:544
	ds_write_b16_d16_hi v235, v97 offset:816
	ds_write_b16 v235, v98 offset:1088
	ds_write_b16_d16_hi v235, v98 offset:1360
	ds_write_b16 v235, v99 offset:1632
	ds_write_b16_d16_hi v235, v99 offset:1904
	s_waitcnt vmcnt(24)
	ds_write_b16 v235, v100 offset:32
	ds_write_b16_d16_hi v235, v100 offset:304
	ds_write_b16 v235, v101 offset:576
	ds_write_b16_d16_hi v235, v101 offset:848
	ds_write_b16 v235, v102 offset:1120
	ds_write_b16_d16_hi v235, v102 offset:1392
	ds_write_b16 v235, v103 offset:1664
	ds_write_b16_d16_hi v235, v103 offset:1936
	s_waitcnt vmcnt(23)
	ds_write_b16 v235, v104 offset:64
	ds_write_b16_d16_hi v235, v104 offset:336
	ds_write_b16 v235, v105 offset:608
	ds_write_b16_d16_hi v235, v105 offset:880
	ds_write_b16 v235, v106 offset:1152
	ds_write_b16_d16_hi v235, v106 offset:1424
	ds_write_b16 v235, v107 offset:1696
	ds_write_b16_d16_hi v235, v107 offset:1968
	s_waitcnt vmcnt(22)
	ds_write_b16 v235, v108 offset:96
	ds_write_b16_d16_hi v235, v108 offset:368
	ds_write_b16 v235, v109 offset:640
	ds_write_b16_d16_hi v235, v109 offset:912
	ds_write_b16 v235, v110 offset:1184
	ds_write_b16_d16_hi v235, v110 offset:1456
	ds_write_b16 v235, v111 offset:1728
	ds_write_b16_d16_hi v235, v111 offset:2000
	s_waitcnt vmcnt(21)
	ds_write_b16 v235, v112 offset:128
	ds_write_b16_d16_hi v235, v112 offset:400
	ds_write_b16 v235, v113 offset:672
	ds_write_b16_d16_hi v235, v113 offset:944
	ds_write_b16 v235, v114 offset:1216
	ds_write_b16_d16_hi v235, v114 offset:1488
	ds_write_b16 v235, v115 offset:1760
	ds_write_b16_d16_hi v235, v115 offset:2032
	s_waitcnt vmcnt(20)
	ds_write_b16 v235, v116 offset:160
	ds_write_b16_d16_hi v235, v116 offset:432
	ds_write_b16 v235, v117 offset:704
	ds_write_b16_d16_hi v235, v117 offset:976
	ds_write_b16 v235, v118 offset:1248
	ds_write_b16_d16_hi v235, v118 offset:1520
	ds_write_b16 v235, v119 offset:1792
	ds_write_b16_d16_hi v235, v119 offset:2064
	s_waitcnt vmcnt(19)
	ds_write_b16 v235, v120 offset:192
	ds_write_b16_d16_hi v235, v120 offset:464
	ds_write_b16 v235, v121 offset:736
	ds_write_b16_d16_hi v235, v121 offset:1008
	ds_write_b16 v235, v122 offset:1280
	ds_write_b16_d16_hi v235, v122 offset:1552
	ds_write_b16 v235, v123 offset:1824
	ds_write_b16_d16_hi v235, v123 offset:2096
	s_waitcnt vmcnt(18)
	ds_write_b16 v235, v124 offset:224
	ds_write_b16_d16_hi v235, v124 offset:496
	ds_write_b16 v235, v125 offset:768
	ds_write_b16_d16_hi v235, v125 offset:1040
	ds_write_b16 v235, v126 offset:1312
	ds_write_b16_d16_hi v235, v126 offset:1584
	ds_write_b16 v235, v127 offset:1856
	ds_write_b16_d16_hi v235, v127 offset:2128
	s_waitcnt lgkmcnt(0)
	s_barrier
	s_lshl_b64 s[4:5], s[6:7], 15
	s_lshl_b64 s[6:7], s[6:7], 6
	v_ashrrev_i32_e32 v75, 31, v74
	v_readlane_b32 s14, v252, 12
	s_mov_b32 s10, 0
	v_lshl_add_u64 v[76:77], v[68:69], 0, s[4:5]
	v_lshl_add_u64 v[78:79], s[6:7], 0, v[74:75]
	s_mov_b32 s6, 0
	s_movk_i32 s7, 0x3000
	s_movk_i32 s12, 0x1000
	v_readlane_b32 s15, v252, 13
	s_waitcnt vmcnt(16)
	ds_write_b64 v253, v[80:81]
	ds_write_b64 v253, v[82:83] offset:512
	s_waitcnt vmcnt(15)
	v_lshlrev_b32_e32 v80, 16, v24
	v_and_b32_e32 v81, 0xffff0000, v24
	v_lshlrev_b32_e32 v82, 16, v25
	v_and_b32_e32 v83, 0xffff0000, v25
	v_lshlrev_b32_e32 v84, 16, v26
	v_and_b32_e32 v85, 0xffff0000, v26
	v_lshlrev_b32_e32 v86, 16, v27
	v_and_b32_e32 v87, 0xffff0000, v27
	s_waitcnt vmcnt(14)
	v_lshlrev_b32_e32 v88, 16, v28
	v_and_b32_e32 v89, 0xffff0000, v28
	v_lshlrev_b32_e32 v90, 16, v29
	v_and_b32_e32 v91, 0xffff0000, v29
	v_lshlrev_b32_e32 v92, 16, v30
	v_and_b32_e32 v93, 0xffff0000, v30
	v_lshlrev_b32_e32 v94, 16, v31
	v_and_b32_e32 v95, 0xffff0000, v31
	s_waitcnt vmcnt(13)
	v_lshlrev_b32_e32 v96, 16, v32
	v_and_b32_e32 v97, 0xffff0000, v32
	v_lshlrev_b32_e32 v98, 16, v33
	v_and_b32_e32 v99, 0xffff0000, v33
	v_lshlrev_b32_e32 v100, 16, v34
	v_and_b32_e32 v101, 0xffff0000, v34
	v_lshlrev_b32_e32 v102, 16, v35
	v_and_b32_e32 v103, 0xffff0000, v35
	s_waitcnt vmcnt(12)
	v_lshlrev_b32_e32 v104, 16, v36
	v_and_b32_e32 v105, 0xffff0000, v36
	v_lshlrev_b32_e32 v106, 16, v37
	s_waitcnt vmcnt(11)
	v_lshlrev_b32_e32 v108, 16, v40
	v_and_b32_e32 v109, 0xffff0000, v40
	v_lshlrev_b32_e32 v110, 16, v41
	v_and_b32_e32 v111, 0xffff0000, v41
	v_lshlrev_b32_e32 v112, 16, v42
	v_and_b32_e32 v113, 0xffff0000, v42
	v_lshlrev_b32_e32 v114, 16, v43
	v_and_b32_e32 v115, 0xffff0000, v43
	s_waitcnt vmcnt(10)
	v_lshlrev_b32_e32 v116, 16, v44
	v_and_b32_e32 v117, 0xffff0000, v44
	v_lshlrev_b32_e32 v118, 16, v45
	v_and_b32_e32 v119, 0xffff0000, v45
	v_lshlrev_b32_e32 v120, 16, v46
	v_and_b32_e32 v121, 0xffff0000, v46
	v_lshlrev_b32_e32 v122, 16, v47
	v_and_b32_e32 v123, 0xffff0000, v47
	s_waitcnt vmcnt(9)
	v_lshlrev_b32_e32 v124, 16, v48
	v_and_b32_e32 v125, 0xffff0000, v48
	v_lshlrev_b32_e32 v126, 16, v49
	v_and_b32_e32 v127, 0xffff0000, v49
	v_lshlrev_b32_e32 v130, 16, v50
	v_and_b32_e32 v131, 0xffff0000, v50
	v_lshlrev_b32_e32 v132, 16, v51
	v_and_b32_e32 v133, 0xffff0000, v51
	v_and_b32_e32 v107, 0xffff0000, v37
	v_lshlrev_b32_e32 v134, 16, v38
	v_and_b32_e32 v135, 0xffff0000, v38
	v_lshlrev_b32_e32 v136, 16, v39
	v_and_b32_e32 v137, 0xffff0000, v39
	s_waitcnt vmcnt(8)
	v_lshlrev_b32_e32 v138, 16, v52
	v_and_b32_e32 v139, 0xffff0000, v52
	v_lshlrev_b32_e32 v140, 16, v53
	v_and_b32_e32 v141, 0xffff0000, v53
	v_lshlrev_b32_e32 v142, 16, v54
	v_and_b32_e32 v143, 0xffff0000, v54
	v_lshlrev_b32_e32 v144, 16, v55
	v_and_b32_e32 v145, 0xffff0000, v55
	s_waitcnt vmcnt(7)
	v_lshlrev_b32_e32 v146, 16, v56
	v_and_b32_e32 v147, 0xffff0000, v56
	v_lshlrev_b32_e32 v148, 16, v57
	v_and_b32_e32 v149, 0xffff0000, v57
	v_lshlrev_b32_e32 v150, 16, v58
	v_and_b32_e32 v151, 0xffff0000, v58
	v_lshlrev_b32_e32 v152, 16, v59
	v_and_b32_e32 v153, 0xffff0000, v59
	s_waitcnt vmcnt(6)
	v_lshlrev_b32_e32 v154, 16, v60
	v_and_b32_e32 v155, 0xffff0000, v60
	v_lshlrev_b32_e32 v156, 16, v61
	v_and_b32_e32 v157, 0xffff0000, v61
	v_lshlrev_b32_e32 v158, 16, v62
	v_and_b32_e32 v159, 0xffff0000, v62
	v_lshlrev_b32_e32 v160, 16, v63
	v_and_b32_e32 v161, 0xffff0000, v63
	s_waitcnt vmcnt(5)
	v_lshlrev_b32_e32 v168, 16, v20
	v_and_b32_e32 v169, 0xffff0000, v20
	v_lshlrev_b32_e32 v170, 16, v21
	v_and_b32_e32 v171, 0xffff0000, v21
	v_lshlrev_b32_e32 v172, 16, v22
	v_and_b32_e32 v173, 0xffff0000, v22
	v_lshlrev_b32_e32 v174, 16, v23
	v_and_b32_e32 v175, 0xffff0000, v23
	s_waitcnt vmcnt(2)
	v_lshlrev_b32_e32 v176, 16, v16
	v_and_b32_e32 v177, 0xffff0000, v16
	v_lshlrev_b32_e32 v178, 16, v17
	v_and_b32_e32 v179, 0xffff0000, v17
	v_lshlrev_b32_e32 v180, 16, v18
	v_and_b32_e32 v181, 0xffff0000, v18
	v_lshlrev_b32_e32 v182, 16, v19
	v_and_b32_e32 v183, 0xffff0000, v19
	v_lshlrev_b32_e32 v184, 16, v12
	v_and_b32_e32 v185, 0xffff0000, v12
	v_lshlrev_b32_e32 v186, 16, v13
	v_and_b32_e32 v187, 0xffff0000, v13
	v_lshlrev_b32_e32 v188, 16, v14
	v_and_b32_e32 v189, 0xffff0000, v14
	v_lshlrev_b32_e32 v190, 16, v15
	v_and_b32_e32 v191, 0xffff0000, v15
	s_waitcnt vmcnt(1)
	v_lshlrev_b32_e32 v192, 16, v8
	v_and_b32_e32 v193, 0xffff0000, v8
	v_lshlrev_b32_e32 v194, 16, v9
	v_and_b32_e32 v195, 0xffff0000, v9
	v_lshlrev_b32_e32 v196, 16, v10
	v_and_b32_e32 v197, 0xffff0000, v10
	v_lshlrev_b32_e32 v198, 16, v11
	v_and_b32_e32 v199, 0xffff0000, v11
	v_lshlrev_b32_e32 v200, 16, v4
	v_and_b32_e32 v201, 0xffff0000, v4
	v_lshlrev_b32_e32 v202, 16, v5
	v_and_b32_e32 v203, 0xffff0000, v5
	v_lshlrev_b32_e32 v204, 16, v6
	v_and_b32_e32 v205, 0xffff0000, v6
	v_lshlrev_b32_e32 v206, 16, v7
	v_and_b32_e32 v207, 0xffff0000, v7
	s_waitcnt vmcnt(0)
	v_lshlrev_b32_e32 v208, 16, v0
	v_and_b32_e32 v209, 0xffff0000, v0
	v_lshlrev_b32_e32 v210, 16, v1
	v_and_b32_e32 v211, 0xffff0000, v1
	v_lshlrev_b32_e32 v212, 16, v2
	v_and_b32_e32 v213, 0xffff0000, v2
	v_lshlrev_b32_e32 v214, 16, v3
	v_and_b32_e32 v215, 0xffff0000, v3
	.p2alignl 6, 3212836864

.LBB0_2104:
	s_or_b64 exec, exec, s[16:17]
	s_xor_b64 s[16:17], s[14:15], -1
	s_mov_b32 s20, 1
	s_mov_b64 s[14:15], 0
	s_and_b64 vcc, exec, s[16:17]
	s_cbranch_vccnz .LBB0_2102
	.p2alignl 6, 3212836864

.LBB0_2225:
	s_and_b32 s6, s2, 7
	v_lshl_add_u32 v0, s6, 8, v201
	v_ashrrev_i32_e32 v1, 31, v0
	v_lshlrev_b64 v[0:1], 12, v[0:1]
	s_and_b32 s6, s5, 0xffffff00
	v_lshl_add_u64 v[170:171], v[160:161], 0, v[0:1]
	v_add_u32_e32 v0, s6, v175
	s_and_b32 s6, s4, 7
	v_ashrrev_i32_e32 v1, 31, v0
	s_or_b32 s6, s6, s3
	v_lshlrev_b64 v[0:1], 12, v[0:1]
	s_lshl_b32 s6, s6, 8
	v_lshl_add_u64 v[172:173], v[168:169], 0, v[0:1]
	v_add_u32_e32 v0, s6, v175
	s_lshl_b32 s7, s4, 5
	v_ashrrev_i32_e32 v1, 31, v0
	s_and_b32 s7, s7, 0xffffff00
	v_add_u32_e32 v2, s7, v175
	v_lshlrev_b64 v[0:1], 12, v[0:1]
	s_waitcnt vmcnt(0) lgkmcnt(0)
	s_barrier
	v_and_b32_e32 v238, 0xff, v163
	v_add_u32_e32 v239, s6, v238
	v_lshlrev_b32_e32 v239, 7, v239
	v_add_u32_e32 v239, 0x1911b600, v239
	global_load_dwordx4 v[64:67], v239, s[0:1]
	global_load_dwordx4 v[68:71], v239, s[0:1] offset:16
	global_load_dwordx4 v[72:75], v239, s[0:1] offset:32
	global_load_dwordx4 v[76:79], v239, s[0:1] offset:48
	global_load_dwordx4 v[80:83], v239, s[0:1] offset:64
	global_load_dwordx4 v[84:87], v239, s[0:1] offset:80
	global_load_dwordx4 v[88:91], v239, s[0:1] offset:96
	global_load_dwordx4 v[92:95], v239, s[0:1] offset:112
	v_lshlrev_b32_e32 v238, 2, v238
	v_add_u32_e32 v238, 0x20020, v238
	v_mov_b32_e32 v250, 0x20020
	v_ashrrev_i32_e32 v3, 31, v2
	v_lshl_add_u64 v[0:1], v[154:155], 0, v[0:1]
	v_readfirstlane_b32 s8, v180
	s_mov_b32 m0, s8
	s_nop 0
	global_load_lds_dwordx4 v[0:1], off
	s_mov_b64 s[12:13], 0x80000
	v_lshlrev_b64 v[2:3], 12, v[2:3]
	v_lshl_add_u64 v[4:5], v[0:1], 0, s[12:13]
	s_add_i32 s9, s8, 0x2000
	s_mov_b32 m0, s9
	s_nop 0
	global_load_lds_dwordx4 v[4:5], off
	v_lshl_add_u64 v[2:3], v[156:157], 0, v[2:3]
	s_add_i32 s9, s8, 0x4000
	s_mov_b32 m0, s9
	s_nop 0
	global_load_lds_dwordx4 v[2:3], off
	v_lshl_add_u64 v[4:5], v[2:3], 0, s[12:13]
	s_add_i32 s9, s8, 0x6000
	s_mov_b32 m0, s9
	s_nop 0
	global_load_lds_dwordx4 v[4:5], off
	s_add_i32 s9, s8, 0x8000
	v_lshl_add_u64 v[4:5], v[0:1], 0, 64
	s_mov_b32 m0, s9
	s_nop 0
	global_load_lds_dwordx4 v[4:5], off
	s_mov_b64 s[10:11], 0x80040
	v_lshl_add_u64 v[4:5], v[0:1], 0, s[10:11]
	s_add_i32 s9, s8, 0xa000
	s_mov_b32 m0, s9
	s_nop 0
	global_load_lds_dwordx4 v[4:5], off
	v_lshl_add_u64 v[4:5], v[2:3], 0, 64
	s_add_i32 s9, s8, 0xc000
	s_mov_b32 m0, s9
	s_nop 0
	global_load_lds_dwordx4 v[4:5], off
	v_lshl_add_u64 v[4:5], v[2:3], 0, s[10:11]
	s_add_i32 s9, s8, 0xe000
	s_mov_b32 m0, s9
	s_nop 0
	global_load_lds_dwordx4 v[4:5], off
	s_mov_b64 s[10:11], 0x80
	s_add_i32 s9, s8, 0x10000
	v_lshl_add_u64 v[4:5], v[0:1], 0, s[10:11]
	s_mov_b32 m0, s9
	s_nop 0
	global_load_lds_dwordx4 v[4:5], off
	s_mov_b64 s[14:15], 0x80080
	v_lshl_add_u64 v[0:1], v[0:1], 0, s[14:15]
	s_add_i32 s9, s8, 0x12000
	s_mov_b32 m0, s9
	s_nop 0
	global_load_lds_dwordx4 v[0:1], off
	v_lshl_add_u64 v[0:1], v[2:3], 0, s[10:11]
	s_add_i32 s9, s8, 0x14000
	s_mov_b32 m0, s9
	s_nop 0
	global_load_lds_dwordx4 v[0:1], off
	v_lshl_add_u64 v[0:1], v[2:3], 0, s[14:15]
	s_add_i32 s8, s8, 0x16000
	s_mov_b32 m0, s8
	s_nop 0
	global_load_lds_dwordx4 v[0:1], off
	s_waitcnt vmcnt(12)
	v_add_f32_e32 v64, v64, v65
	v_add_f32_e32 v64, v64, v66
	v_add_f32_e32 v64, v64, v67
	v_add_f32_e32 v64, v64, v68
	v_add_f32_e32 v64, v64, v69
	v_add_f32_e32 v64, v64, v70
	v_add_f32_e32 v64, v64, v71
	v_add_f32_e32 v64, v64, v72
	v_add_f32_e32 v64, v64, v73
	v_add_f32_e32 v64, v64, v74
	v_add_f32_e32 v64, v64, v75
	v_add_f32_e32 v64, v64, v76
	v_add_f32_e32 v64, v64, v77
	v_add_f32_e32 v64, v64, v78
	v_add_f32_e32 v64, v64, v79
	v_add_f32_e32 v64, v64, v80
	v_add_f32_e32 v64, v64, v81
	v_add_f32_e32 v64, v64, v82
	v_add_f32_e32 v64, v64, v83
	v_add_f32_e32 v64, v64, v84
	v_add_f32_e32 v64, v64, v85
	v_add_f32_e32 v64, v64, v86
	v_add_f32_e32 v64, v64, v87
	v_add_f32_e32 v64, v64, v88
	v_add_f32_e32 v64, v64, v89
	v_add_f32_e32 v64, v64, v90
	v_add_f32_e32 v64, v64, v91
	v_add_f32_e32 v64, v64, v92
	v_add_f32_e32 v64, v64, v93
	v_add_f32_e32 v64, v64, v94
	v_add_f32_e32 v64, v64, v95
	v_fmamk_f32 v64, v64, 0x3a000000, v162
	v_mul_f32_e32 v65, 0x4b800000, v64
	v_cmp_gt_f32_e32 vcc, 0x800000, v64
	s_nop 1
	v_cndmask_b32_e32 v64, v64, v65, vcc
	v_rsq_f32_e32 v64, v64
	s_nop 0
	v_mul_f32_e32 v65, 0x45800000, v64
	v_cndmask_b32_e32 v64, v64, v65, vcc
	ds_write_b32 v238, v64
	v_mov_b32_e32 v130, 0
	v_mov_b32_e32 v134, 0
	v_mov_b32_e32 v0, 0
	s_mov_b32 s8, 0x18000
	v_mov_b32_e32 v1, v0
	v_mov_b32_e32 v2, v0
	v_mov_b32_e32 v3, v0
	v_mov_b32_e32 v4, v0
	v_mov_b32_e32 v5, v0
	v_mov_b32_e32 v6, v0
	v_mov_b32_e32 v7, v0
	v_mov_b32_e32 v8, v0
	v_mov_b32_e32 v9, v0
	v_mov_b32_e32 v10, v0
	v_mov_b32_e32 v11, v0
	v_mov_b32_e32 v12, v0
	v_mov_b32_e32 v13, v0
	v_mov_b32_e32 v14, v0
	v_mov_b32_e32 v15, v0
	v_mov_b32_e32 v16, v0
	v_mov_b32_e32 v17, v0
	v_mov_b32_e32 v18, v0
	v_mov_b32_e32 v19, v0
	v_mov_b32_e32 v20, v0
	v_mov_b32_e32 v21, v0
	v_mov_b32_e32 v22, v0
	v_mov_b32_e32 v23, v0
	v_mov_b32_e32 v24, v0
	v_mov_b32_e32 v25, v0
	v_mov_b32_e32 v26, v0
	v_mov_b32_e32 v27, v0
	v_mov_b32_e32 v28, v0
	v_mov_b32_e32 v29, v0
	v_mov_b32_e32 v30, v0
	v_mov_b32_e32 v31, v0
	v_mov_b32_e32 v32, v0
	v_mov_b32_e32 v33, v0
	v_mov_b32_e32 v34, v0
	v_mov_b32_e32 v35, v0
	v_mov_b32_e32 v36, v0
	v_mov_b32_e32 v37, v0
	v_mov_b32_e32 v38, v0
	v_mov_b32_e32 v39, v0
	v_mov_b32_e32 v40, v0
	v_mov_b32_e32 v41, v0
	v_mov_b32_e32 v42, v0
	v_mov_b32_e32 v43, v0
	v_mov_b32_e32 v44, v0
	v_mov_b32_e32 v45, v0
	v_mov_b32_e32 v46, v0
	v_mov_b32_e32 v47, v0
	v_mov_b32_e32 v48, v0
	v_mov_b32_e32 v49, v0
	v_mov_b32_e32 v50, v0
	v_mov_b32_e32 v51, v0
	v_mov_b32_e32 v52, v0
	v_mov_b32_e32 v53, v0
	v_mov_b32_e32 v54, v0
	v_mov_b32_e32 v55, v0
	v_mov_b32_e32 v56, v0
	v_mov_b32_e32 v57, v0
	v_mov_b32_e32 v58, v0
	v_mov_b32_e32 v59, v0
	v_mov_b32_e32 v60, v0
	v_mov_b32_e32 v61, v0
	v_mov_b32_e32 v62, v0
	v_mov_b32_e32 v63, v0
	v_mov_b32_e32 v64, v0
	v_mov_b32_e32 v65, v0
	v_mov_b32_e32 v66, v0
	v_mov_b32_e32 v67, v0
	v_mov_b32_e32 v68, v0
	v_mov_b32_e32 v69, v0
	v_mov_b32_e32 v70, v0
	v_mov_b32_e32 v71, v0
	v_mov_b32_e32 v72, v0
	v_mov_b32_e32 v73, v0
	v_mov_b32_e32 v74, v0
	v_mov_b32_e32 v75, v0
	v_mov_b32_e32 v76, v0
	v_mov_b32_e32 v77, v0
	v_mov_b32_e32 v78, v0
	v_mov_b32_e32 v79, v0
	v_mov_b32_e32 v80, v0
	v_mov_b32_e32 v81, v0
	v_mov_b32_e32 v82, v0
	v_mov_b32_e32 v83, v0
	v_mov_b32_e32 v84, v0
	v_mov_b32_e32 v85, v0
	v_mov_b32_e32 v86, v0
	v_mov_b32_e32 v87, v0
	v_mov_b32_e32 v88, v0
	v_mov_b32_e32 v89, v0
	v_mov_b32_e32 v90, v0
	v_mov_b32_e32 v91, v0
	v_mov_b32_e32 v92, v0
	v_mov_b32_e32 v93, v0
	v_mov_b32_e32 v94, v0
	v_mov_b32_e32 v95, v0
	v_mov_b32_e32 v96, v0
	v_mov_b32_e32 v97, v0
	v_mov_b32_e32 v98, v0
	v_mov_b32_e32 v99, v0
	v_mov_b32_e32 v100, v0
	v_mov_b32_e32 v101, v0
	v_mov_b32_e32 v102, v0
	v_mov_b32_e32 v103, v0
	v_mov_b32_e32 v104, v0
	v_mov_b32_e32 v105, v0
	v_mov_b32_e32 v106, v0
	v_mov_b32_e32 v107, v0
	v_mov_b32_e32 v108, v0
	v_mov_b32_e32 v109, v0
	v_mov_b32_e32 v110, v0
	v_mov_b32_e32 v111, v0
	v_mov_b32_e32 v112, v0
	v_mov_b32_e32 v113, v0
	v_mov_b32_e32 v114, v0
	v_mov_b32_e32 v115, v0
	v_mov_b32_e32 v116, v0
	v_mov_b32_e32 v117, v0
	v_mov_b32_e32 v118, v0
	v_mov_b32_e32 v119, v0
	v_mov_b32_e32 v120, v0
	v_mov_b32_e32 v121, v0
	v_mov_b32_e32 v122, v0
	v_mov_b32_e32 v123, v0
	v_mov_b32_e32 v124, v0
	v_mov_b32_e32 v125, v0
	v_mov_b32_e32 v126, v0
	v_mov_b32_e32 v127, v0
	v_mov_b32_e32 v135, v134
	v_mov_b32_e32 v136, v134
	v_mov_b32_e32 v137, v134
	v_mov_b32_e32 v138, v134
	v_mov_b32_e32 v139, v134
	v_mov_b32_e32 v140, v134
	v_mov_b32_e32 v141, v134
	v_mov_b32_e32 v146, v134
	v_mov_b32_e32 v147, v134
	v_mov_b32_e32 v148, v134
	v_mov_b32_e32 v149, v134
	v_mov_b32_e32 v150, v134
	v_mov_b32_e32 v151, v134
	v_mov_b32_e32 v152, v134
	v_mov_b32_e32 v153, v134
	v_mov_b32_e32 v131, v130
	v_mov_b32_e32 v132, v130
	v_mov_b32_e32 v133, v130
	v_mov_b32_e32 v142, v130
	v_mov_b32_e32 v143, v130
	v_mov_b32_e32 v144, v130
	v_mov_b32_e32 v145, v130
	.p2alignl 6, 3212836864

.Lpf_after_up:
	v_mov_b32_e32 v130, 0
	v_mov_b32_e32 v134, 0
	v_mov_b32_e32 v0, 0
	s_mov_b32 s18, 0x18000
	v_mov_b32_e32 v1, v0
	v_mov_b32_e32 v2, v0
	v_mov_b32_e32 v3, v0
	v_mov_b32_e32 v4, v0
	v_mov_b32_e32 v5, v0
	v_mov_b32_e32 v6, v0
	v_mov_b32_e32 v7, v0
	v_mov_b32_e32 v8, v0
	v_mov_b32_e32 v9, v0
	v_mov_b32_e32 v10, v0
	v_mov_b32_e32 v11, v0
	v_mov_b32_e32 v12, v0
	v_mov_b32_e32 v13, v0
	v_mov_b32_e32 v14, v0
	v_mov_b32_e32 v15, v0
	v_mov_b32_e32 v16, v0
	v_mov_b32_e32 v17, v0
	v_mov_b32_e32 v18, v0
	v_mov_b32_e32 v19, v0
	v_mov_b32_e32 v20, v0
	v_mov_b32_e32 v21, v0
	v_mov_b32_e32 v22, v0
	v_mov_b32_e32 v23, v0
	v_mov_b32_e32 v24, v0
	v_mov_b32_e32 v25, v0
	v_mov_b32_e32 v26, v0
	v_mov_b32_e32 v27, v0
	v_mov_b32_e32 v28, v0
	v_mov_b32_e32 v29, v0
	v_mov_b32_e32 v30, v0
	v_mov_b32_e32 v31, v0
	v_mov_b32_e32 v32, v0
	v_mov_b32_e32 v33, v0
	v_mov_b32_e32 v34, v0
	v_mov_b32_e32 v35, v0
	v_mov_b32_e32 v36, v0
	v_mov_b32_e32 v37, v0
	v_mov_b32_e32 v38, v0
	v_mov_b32_e32 v39, v0
	v_mov_b32_e32 v40, v0
	v_mov_b32_e32 v41, v0
	v_mov_b32_e32 v42, v0
	v_mov_b32_e32 v43, v0
	v_mov_b32_e32 v44, v0
	v_mov_b32_e32 v45, v0
	v_mov_b32_e32 v46, v0
	v_mov_b32_e32 v47, v0
	v_mov_b32_e32 v48, v0
	v_mov_b32_e32 v49, v0
	v_mov_b32_e32 v50, v0
	v_mov_b32_e32 v51, v0
	v_mov_b32_e32 v52, v0
	v_mov_b32_e32 v53, v0
	v_mov_b32_e32 v54, v0
	v_mov_b32_e32 v55, v0
	v_mov_b32_e32 v56, v0
	v_mov_b32_e32 v57, v0
	v_mov_b32_e32 v58, v0
	v_mov_b32_e32 v59, v0
	v_mov_b32_e32 v60, v0
	v_mov_b32_e32 v61, v0
	v_mov_b32_e32 v62, v0
	v_mov_b32_e32 v63, v0
	v_mov_b32_e32 v64, v0
	v_mov_b32_e32 v65, v0
	v_mov_b32_e32 v66, v0
	v_mov_b32_e32 v67, v0
	v_mov_b32_e32 v68, v0
	v_mov_b32_e32 v69, v0
	v_mov_b32_e32 v70, v0
	v_mov_b32_e32 v71, v0
	v_mov_b32_e32 v72, v0
	v_mov_b32_e32 v73, v0
	v_mov_b32_e32 v74, v0
	v_mov_b32_e32 v75, v0
	v_mov_b32_e32 v76, v0
	v_mov_b32_e32 v77, v0
	v_mov_b32_e32 v78, v0
	v_mov_b32_e32 v79, v0
	v_mov_b32_e32 v80, v0
	v_mov_b32_e32 v81, v0
	v_mov_b32_e32 v82, v0
	v_mov_b32_e32 v83, v0
	v_mov_b32_e32 v84, v0
	v_mov_b32_e32 v85, v0
	v_mov_b32_e32 v86, v0
	v_mov_b32_e32 v87, v0
	v_mov_b32_e32 v88, v0
	v_mov_b32_e32 v89, v0
	v_mov_b32_e32 v90, v0
	v_mov_b32_e32 v91, v0
	v_mov_b32_e32 v92, v0
	v_mov_b32_e32 v93, v0
	v_mov_b32_e32 v94, v0
	v_mov_b32_e32 v95, v0
	v_mov_b32_e32 v96, v0
	v_mov_b32_e32 v97, v0
	v_mov_b32_e32 v98, v0
	v_mov_b32_e32 v99, v0
	v_mov_b32_e32 v100, v0
	v_mov_b32_e32 v101, v0
	v_mov_b32_e32 v102, v0
	v_mov_b32_e32 v103, v0
	v_mov_b32_e32 v104, v0
	v_mov_b32_e32 v105, v0
	v_mov_b32_e32 v106, v0
	v_mov_b32_e32 v107, v0
	v_mov_b32_e32 v108, v0
	v_mov_b32_e32 v109, v0
	v_mov_b32_e32 v110, v0
	v_mov_b32_e32 v111, v0
	v_mov_b32_e32 v112, v0
	v_mov_b32_e32 v113, v0
	v_mov_b32_e32 v114, v0
	v_mov_b32_e32 v115, v0
	v_mov_b32_e32 v116, v0
	v_mov_b32_e32 v117, v0
	v_mov_b32_e32 v118, v0
	v_mov_b32_e32 v119, v0
	v_mov_b32_e32 v120, v0
	v_mov_b32_e32 v121, v0
	v_mov_b32_e32 v122, v0
	v_mov_b32_e32 v123, v0
	v_mov_b32_e32 v124, v0
	v_mov_b32_e32 v125, v0
	v_mov_b32_e32 v126, v0
	v_mov_b32_e32 v127, v0
	v_mov_b32_e32 v135, v134
	v_mov_b32_e32 v136, v134
	v_mov_b32_e32 v137, v134
	v_mov_b32_e32 v138, v134
	v_mov_b32_e32 v139, v134
	v_mov_b32_e32 v140, v134
	v_mov_b32_e32 v141, v134
	v_mov_b32_e32 v146, v134
	v_mov_b32_e32 v147, v134
	v_mov_b32_e32 v148, v134
	v_mov_b32_e32 v149, v134
	v_mov_b32_e32 v150, v134
	v_mov_b32_e32 v151, v134
	v_mov_b32_e32 v152, v134
	v_mov_b32_e32 v153, v134
	v_mov_b32_e32 v131, v130
	v_mov_b32_e32 v132, v130
	v_mov_b32_e32 v133, v130
	v_mov_b32_e32 v142, v130
	v_mov_b32_e32 v143, v130
	v_mov_b32_e32 v144, v130
	v_mov_b32_e32 v145, v130
	.p2alignl 6, 3212836864

.LBB0_2550:
	s_and_b32 s3, s0, 7
	v_lshl_add_u32 v0, s3, 8, v201
	s_and_b32 s3, s2, 0xffffff00
	v_mad_i64_i32 v[170:171], s[4:5], v0, s7, v[160:161]
	v_add_u32_e32 v0, s3, v175
	s_and_b32 s3, s6, 7
	v_mad_i64_i32 v[172:173], s[4:5], v0, s7, v[168:169]
	s_or_b32 s3, s3, s1
	s_lshl_b32 s3, s3, 8
	s_lshl_b32 s4, s6, 5
	v_add_u32_e32 v0, s3, v175
	s_and_b32 s4, s4, 0xffffff00
	s_waitcnt vmcnt(0) lgkmcnt(0)
	s_barrier
	v_add_u32_e32 v2, s4, v175
	v_mad_i64_i32 v[0:1], s[8:9], v0, s7, v[154:155]
	v_readfirstlane_b32 s5, v180
	s_mov_b32 m0, s5
	s_nop 0
	global_load_lds_dwordx4 v[0:1], off
	v_mad_i64_i32 v[2:3], s[8:9], v2, s7, v[156:157]
	v_lshl_add_u64 v[4:5], v[0:1], 0, s[10:11]
	s_add_i32 s7, s5, 0x2000
	s_mov_b32 m0, s7
	s_nop 0
	global_load_lds_dwordx4 v[4:5], off
	s_add_i32 s7, s5, 0x4000
	s_mov_b32 m0, s7
	s_nop 0
	global_load_lds_dwordx4 v[2:3], off
	v_lshl_add_u64 v[4:5], v[2:3], 0, s[10:11]
	s_add_i32 s7, s5, 0x6000
	s_mov_b32 m0, s7
	s_nop 0
	global_load_lds_dwordx4 v[4:5], off
	s_add_i32 s7, s5, 0x8000
	v_lshl_add_u64 v[4:5], v[0:1], 0, 64
	s_mov_b32 m0, s7
	s_nop 0
	global_load_lds_dwordx4 v[4:5], off
	s_mov_b64 s[8:9], 0xb0040
	v_lshl_add_u64 v[4:5], v[0:1], 0, s[8:9]
	s_add_i32 s7, s5, 0xa000
	s_mov_b32 m0, s7
	s_nop 0
	global_load_lds_dwordx4 v[4:5], off
	v_lshl_add_u64 v[4:5], v[2:3], 0, 64
	s_add_i32 s7, s5, 0xc000
	s_mov_b32 m0, s7
	s_nop 0
	global_load_lds_dwordx4 v[4:5], off
	v_lshl_add_u64 v[4:5], v[2:3], 0, s[8:9]
	s_add_i32 s7, s5, 0xe000
	s_mov_b32 m0, s7
	s_nop 0
	global_load_lds_dwordx4 v[4:5], off
	s_mov_b64 s[8:9], 0x80
	s_add_i32 s7, s5, 0x10000
	v_lshl_add_u64 v[4:5], v[0:1], 0, s[8:9]
	s_mov_b32 m0, s7
	s_nop 0
	global_load_lds_dwordx4 v[4:5], off
	s_mov_b64 s[12:13], 0xb0080
	v_lshl_add_u64 v[0:1], v[0:1], 0, s[12:13]
	s_add_i32 s7, s5, 0x12000
	s_mov_b32 m0, s7
	s_nop 0
	global_load_lds_dwordx4 v[0:1], off
	v_lshl_add_u64 v[0:1], v[2:3], 0, s[8:9]
	s_add_i32 s7, s5, 0x14000
	s_mov_b32 m0, s7
	s_nop 0
	global_load_lds_dwordx4 v[0:1], off
	v_lshl_add_u64 v[0:1], v[2:3], 0, s[12:13]
	s_add_i32 s5, s5, 0x16000
	s_mov_b32 m0, s5
	s_nop 0
	global_load_lds_dwordx4 v[0:1], off
	v_mov_b32_e32 v130, 0
	v_mov_b32_e32 v134, 0
	v_mov_b32_e32 v0, 0
	s_mov_b32 s5, 0x18000
	v_mov_b32_e32 v1, v0
	v_mov_b32_e32 v2, v0
	v_mov_b32_e32 v3, v0
	v_mov_b32_e32 v4, v0
	v_mov_b32_e32 v5, v0
	v_mov_b32_e32 v6, v0
	v_mov_b32_e32 v7, v0
	v_mov_b32_e32 v8, v0
	v_mov_b32_e32 v9, v0
	v_mov_b32_e32 v10, v0
	v_mov_b32_e32 v11, v0
	v_mov_b32_e32 v12, v0
	v_mov_b32_e32 v13, v0
	v_mov_b32_e32 v14, v0
	v_mov_b32_e32 v15, v0
	v_mov_b32_e32 v16, v0
	v_mov_b32_e32 v17, v0
	v_mov_b32_e32 v18, v0
	v_mov_b32_e32 v19, v0
	v_mov_b32_e32 v20, v0
	v_mov_b32_e32 v21, v0
	v_mov_b32_e32 v22, v0
	v_mov_b32_e32 v23, v0
	v_mov_b32_e32 v24, v0
	v_mov_b32_e32 v25, v0
	v_mov_b32_e32 v26, v0
	v_mov_b32_e32 v27, v0
	v_mov_b32_e32 v28, v0
	v_mov_b32_e32 v29, v0
	v_mov_b32_e32 v30, v0
	v_mov_b32_e32 v31, v0
	v_mov_b32_e32 v32, v0
	v_mov_b32_e32 v33, v0
	v_mov_b32_e32 v34, v0
	v_mov_b32_e32 v35, v0
	v_mov_b32_e32 v36, v0
	v_mov_b32_e32 v37, v0
	v_mov_b32_e32 v38, v0
	v_mov_b32_e32 v39, v0
	v_mov_b32_e32 v40, v0
	v_mov_b32_e32 v41, v0
	v_mov_b32_e32 v42, v0
	v_mov_b32_e32 v43, v0
	v_mov_b32_e32 v44, v0
	v_mov_b32_e32 v45, v0
	v_mov_b32_e32 v46, v0
	v_mov_b32_e32 v47, v0
	v_mov_b32_e32 v48, v0
	v_mov_b32_e32 v49, v0
	v_mov_b32_e32 v50, v0
	v_mov_b32_e32 v51, v0
	v_mov_b32_e32 v52, v0
	v_mov_b32_e32 v53, v0
	v_mov_b32_e32 v54, v0
	v_mov_b32_e32 v55, v0
	v_mov_b32_e32 v56, v0
	v_mov_b32_e32 v57, v0
	v_mov_b32_e32 v58, v0
	v_mov_b32_e32 v59, v0
	v_mov_b32_e32 v60, v0
	v_mov_b32_e32 v61, v0
	v_mov_b32_e32 v62, v0
	v_mov_b32_e32 v63, v0
	v_mov_b32_e32 v64, v0
	v_mov_b32_e32 v65, v0
	v_mov_b32_e32 v66, v0
	v_mov_b32_e32 v67, v0
	v_mov_b32_e32 v68, v0
	v_mov_b32_e32 v69, v0
	v_mov_b32_e32 v70, v0
	v_mov_b32_e32 v71, v0
	v_mov_b32_e32 v72, v0
	v_mov_b32_e32 v73, v0
	v_mov_b32_e32 v74, v0
	v_mov_b32_e32 v75, v0
	v_mov_b32_e32 v76, v0
	v_mov_b32_e32 v77, v0
	v_mov_b32_e32 v78, v0
	v_mov_b32_e32 v79, v0
	v_mov_b32_e32 v80, v0
	v_mov_b32_e32 v81, v0
	v_mov_b32_e32 v82, v0
	v_mov_b32_e32 v83, v0
	v_mov_b32_e32 v84, v0
	v_mov_b32_e32 v85, v0
	v_mov_b32_e32 v86, v0
	v_mov_b32_e32 v87, v0
	v_mov_b32_e32 v88, v0
	v_mov_b32_e32 v89, v0
	v_mov_b32_e32 v90, v0
	v_mov_b32_e32 v91, v0
	v_mov_b32_e32 v92, v0
	v_mov_b32_e32 v93, v0
	v_mov_b32_e32 v94, v0
	v_mov_b32_e32 v95, v0
	v_mov_b32_e32 v96, v0
	v_mov_b32_e32 v97, v0
	v_mov_b32_e32 v98, v0
	v_mov_b32_e32 v99, v0
	v_mov_b32_e32 v100, v0
	v_mov_b32_e32 v101, v0
	v_mov_b32_e32 v102, v0
	v_mov_b32_e32 v103, v0
	v_mov_b32_e32 v104, v0
	v_mov_b32_e32 v105, v0
	v_mov_b32_e32 v106, v0
	v_mov_b32_e32 v107, v0
	v_mov_b32_e32 v108, v0
	v_mov_b32_e32 v109, v0
	v_mov_b32_e32 v110, v0
	v_mov_b32_e32 v111, v0
	v_mov_b32_e32 v112, v0
	v_mov_b32_e32 v113, v0
	v_mov_b32_e32 v114, v0
	v_mov_b32_e32 v115, v0
	v_mov_b32_e32 v116, v0
	v_mov_b32_e32 v117, v0
	v_mov_b32_e32 v118, v0
	v_mov_b32_e32 v119, v0
	v_mov_b32_e32 v120, v0
	v_mov_b32_e32 v121, v0
	v_mov_b32_e32 v122, v0
	v_mov_b32_e32 v123, v0
	v_mov_b32_e32 v124, v0
	v_mov_b32_e32 v125, v0
	v_mov_b32_e32 v126, v0
	v_mov_b32_e32 v127, v0
	v_mov_b32_e32 v135, v134
	v_mov_b32_e32 v136, v134
	v_mov_b32_e32 v137, v134
	v_mov_b32_e32 v138, v134
	v_mov_b32_e32 v139, v134
	v_mov_b32_e32 v140, v134
	v_mov_b32_e32 v141, v134
	v_mov_b32_e32 v146, v134
	v_mov_b32_e32 v147, v134
	v_mov_b32_e32 v148, v134
	v_mov_b32_e32 v149, v134
	v_mov_b32_e32 v150, v134
	v_mov_b32_e32 v151, v134
	v_mov_b32_e32 v152, v134
	v_mov_b32_e32 v153, v134
	v_mov_b32_e32 v131, v130
	v_mov_b32_e32 v132, v130
	v_mov_b32_e32 v133, v130
	v_mov_b32_e32 v142, v130
	v_mov_b32_e32 v143, v130
	v_mov_b32_e32 v144, v130
	v_mov_b32_e32 v145, v130
	.p2alignl 6, 3212836864
